# fold weight-conversion loops: gain/bias vector loads issued ahead of the next-tile prefetch with one counted wait per tile (was 4-5 full vmcnt(0) drains per tile); stacked
# speedup vs baseline: 1.0063x; 1.0062x over previous
; #define CW_COORD(j, valid, k0, n0) do { if (FOLD) { const int _u = u0 + ((j) >> 3) * G; valid = _u < nunits; n0 = (_u >> 2) << 8; k0 = (_u & 3) * 512 + ((j) & 7) * 64; } \
;                                         else { const int _t = bid + (j) * G; valid = _t < nt_all; k0 = (_t % ntk) << 6; n0 = (_t / ntk) << 8; } } while (0)
; #define CW_LOAD(v, j) do { bool _ok; int _k0, _n0; CW_COORD(j, _ok, _k0, _n0); if (_ok) { _Pragma("unroll") for (int i = 0; i < 8; ++i) v[i] = __builtin_nontemporal_load((const f32x4*)(W + (size_t)(_k0 + lk + 8 * i) * N + _n0 + ln4)); } } while (0)
; template <bool FOLD> ...
;     ...
;     const int G = vG, bid = vbid, ntk = K >> 6, nt_all = ntk * (N >> 8), nunits = (N >> 8) * 4, u0 = vbid;
;     const int lk = tid >> 6, ln4 = (tid & 63) << 2, n = tid >> 1, par = tid & 1;
;     float csum = 0.f, bsum = 0.f;
;     ...
;     f32x4 va[8], vb[8];
;     CW_LOAD(va, 0); CW_LOAD(vb, 1);
;     for (int j = 0;; j += 2) {
;         bool ok; int kk, nn; CW_COORD(j, ok, kk, nn); if (!ok) break;
;         CW_PROC(va, j, 0);
;         CW_PROC(vb, j + 1, 1);
;     }
.LBB0_270:
	v_mov_b32_e32 v66, v210
	s_andn2_b64 vcc, exec, s[4:5]
	s_cbranch_vccnz .LBB0_283
	v_readlane_b32 s0, v251, 28
	s_max_i32 s12, s0, 0x7f
	s_addk_i32 s12, 0xff80
	s_cmpk_gt_u32 s12, 0x7f
	s_cbranch_scc1 .LBB0_282
	v_readlane_b32 s0, v251, 29
	v_readlane_b32 s1, v251, 30
	s_mov_b32 s4, s0
	s_ashr_i32 s5, s0, 31
	v_writelane_b32 v251, s0, 29
	v_ashrrev_i32_e32 v146, 6, v66
	v_lshlrev_b32_e32 v67, 2, v66
	v_writelane_b32 v251, s1, 30
	s_lshl_b64 s[0:1], s[4:5], 3
	s_add_u32 s0, s68, s0
	s_addc_u32 s1, s69, s1
	s_load_dwordx2 s[14:15], s[0:1], 0x98
	v_readlane_b32 s4, v251, 33
	v_readlane_b32 s5, v251, 34
	s_mov_b32 s16, s4
	s_ashr_i32 s17, s4, 31
	s_load_dwordx4 s[4:7], s[0:1], 0x88
	s_lshl_b64 s[0:1], s[16:17], 26
	s_waitcnt lgkmcnt(0)
	s_add_u32 s0, s14, s0
	s_addc_u32 s1, s15, s1
	s_lshl_b64 s[14:15], s[16:17], 13
	s_add_u32 s4, s4, s14
	s_addc_u32 s5, s5, s15
	s_add_u32 s6, s6, s14
	s_mov_b32 s2, s16
	s_addc_u32 s7, s7, s15
	v_writelane_b32 v251, s2, 33
	s_add_u32 s13, s42, 0x20743600
	s_addc_u32 s14, s43, 0
	v_writelane_b32 v251, s3, 34
	s_lshl_b32 s2, s12, 9
	s_and_b32 s2, s2, 0x600
	s_waitcnt vmcnt(0)
	v_add_u32_e32 v18, s2, v146
	s_lshl_b32 s2, s12, 8
	s_and_b32 s2, s2, 0x7c00
	v_and_b32_e32 v0, 0xfc, v67
	s_add_u32 s16, s0, s2
	s_addc_u32 s17, s1, 0
	v_lshlrev_b32_e32 v0, 2, v0
	v_ashrrev_i32_e32 v19, 31, v18
	v_lshl_add_u64 v[20:21], s[16:17], 0, v[0:1]
	v_lshlrev_b64 v[2:3], 15, v[18:19]
	v_lshl_add_u64 v[26:27], v[20:21], 0, v[2:3]
	v_add_co_u32_e32 v6, vcc, s83, v26
	s_mov_b32 s15, 0x80000
	s_nop 0
	v_addc_co_u32_e32 v7, vcc, 0, v27, vcc
	v_add_co_u32_e32 v10, vcc, s15, v26
	s_mov_b32 s16, 0xc0000
	s_nop 0
	v_addc_co_u32_e32 v11, vcc, 0, v27, vcc
	v_add_co_u32_e32 v14, vcc, s16, v26
	s_mov_b32 s2, 0x100000
	s_nop 0
	v_addc_co_u32_e32 v15, vcc, 0, v27, vcc
	v_add_co_u32_e32 v22, vcc, s2, v26
	s_mov_b32 s17, 0x140000
	s_nop 0
	v_addc_co_u32_e32 v23, vcc, 0, v27, vcc
	v_add_co_u32_e32 v28, vcc, s17, v26
	s_mov_b32 s18, 0x180000
	s_nop 0
	v_addc_co_u32_e32 v29, vcc, 0, v27, vcc
	global_load_dwordx4 v[2:5], v[26:27], off nt
	s_nop 0
	global_load_dwordx4 v[6:9], v[6:7], off nt
	s_nop 0
	global_load_dwordx4 v[10:13], v[10:11], off nt
	s_nop 0
	global_load_dwordx4 v[14:17], v[14:15], off nt
	s_nop 0
	global_load_dwordx4 v[22:25], v[22:23], off nt
	s_nop 0
	global_load_dwordx4 v[30:33], v[28:29], off nt
	v_add_co_u32_e32 v28, vcc, s18, v26
	v_add_u32_e32 v18, 64, v18
	s_nop 0
	v_addc_co_u32_e32 v29, vcc, 0, v27, vcc
	s_mov_b32 s19, 0x1c0000
	v_ashrrev_i32_e32 v19, 31, v18
	v_add_co_u32_e32 v26, vcc, s19, v26
	v_lshlrev_b64 v[18:19], 15, v[18:19]
	s_nop 0
	v_addc_co_u32_e32 v27, vcc, 0, v27, vcc
	v_lshl_add_u64 v[58:59], v[20:21], 0, v[18:19]
	global_load_dwordx4 v[38:41], v[28:29], off nt
	global_load_dwordx4 v[46:49], v[26:27], off nt
	v_add_co_u32_e32 v26, vcc, s83, v58
	v_and_b32_e32 v68, 1, v66
	s_nop 0
	v_addc_co_u32_e32 v27, vcc, 0, v59, vcc
	v_add_co_u32_e32 v34, vcc, s15, v58
	global_load_dwordx4 v[18:21], v[58:59], off nt
	s_nop 0
	global_load_dwordx4 v[26:29], v[26:27], off nt
	v_addc_co_u32_e32 v35, vcc, 0, v59, vcc
	v_add_co_u32_e32 v42, vcc, s16, v58
	v_ashrrev_i32_e32 v147, 1, v66
	s_nop 0
	v_addc_co_u32_e32 v43, vcc, 0, v59, vcc
	v_add_co_u32_e32 v50, vcc, s2, v58
	global_load_dwordx4 v[34:37], v[34:35], off nt
	s_nop 0
	global_load_dwordx4 v[42:45], v[42:43], off nt
	v_addc_co_u32_e32 v51, vcc, 0, v59, vcc
	v_add_co_u32_e32 v54, vcc, s17, v58
	v_lshl_add_u64 v[114:115], s[0:1], 0, v[0:1]
	s_nop 0
	v_addc_co_u32_e32 v55, vcc, 0, v59, vcc
	v_add_co_u32_e32 v60, vcc, s18, v58
	global_load_dwordx4 v[50:53], v[50:51], off nt
	s_nop 0
	global_load_dwordx4 v[54:57], v[54:55], off nt
	v_addc_co_u32_e32 v61, vcc, 0, v59, vcc
	v_add_co_u32_e32 v62, vcc, s19, v58
	v_lshlrev_b32_e32 v66, 3, v68
	s_nop 0
	v_addc_co_u32_e32 v63, vcc, 0, v59, vcc
	global_load_dwordx4 v[58:61], v[60:61], off nt
	s_nop 0
	global_load_dwordx4 v[62:65], v[62:63], off nt
	v_readlane_b32 s0, v250, 62
	v_add_u32_e32 v69, 0, v0
	s_movk_i32 s2, 0x404
	v_add_u32_e32 v71, s0, v0
	v_or_b32_e32 v0, 16, v66
	v_lshlrev_b32_e32 v70, 2, v147
	v_bitop3_b32 v150, v67, 4, v205 bitop3:0x6c
	v_mul_lo_u32 v67, v146, s2
	v_mul_u32_u24_e32 v152, 0x404, v0
	v_lshlrev_b32_e32 v0, 5, v68
	v_mov_b32_e32 v122, 0
	s_mov_b32 s23, 0x80000
	s_mov_b32 s24, 0xc0000
	s_mov_b32 s22, 0x100000
	s_mov_b32 s25, 0x140000
	s_mov_b32 s26, 0x180000
	s_mov_b32 s27, 0x1c0000
	s_mov_b32 s15, 3
	v_add_u32_e32 v148, 0, v70
	v_add_u32_e32 v149, s0, v70
	v_cmp_eq_u32_e64 s[0:1], 0, v68
	v_mul_u32_u24_e32 v151, 0x2020, v68
	v_lshl_add_u64 v[116:117], s[4:5], 0, v[0:1]
	v_lshl_add_u64 v[118:119], s[6:7], 0, v[0:1]
	s_movk_i32 s16, 0xc0
	v_add_u32_e32 v153, v69, v67
	v_lshlrev_b32_e32 v0, 1, v66
	v_add_u32_e32 v154, v71, v67
	s_mov_b32 s2, s12
	v_mov_b32_e32 v123, v122
	s_waitcnt vmcnt(0)
	s_branch .LBB0_275

.LBB0_275:
	s_waitcnt lgkmcnt(0)
	v_add_u32_e32 v66, 0x2020, v153
	ds_write2_b32 v153, v2, v3 offset1:1
	ds_write2_b32 v153, v4, v5 offset0:2 offset1:3
	ds_write2_b32 v66, v6, v7 offset1:1
	v_add_u32_e32 v66, 0x2028, v153
	ds_write2_b32 v66, v8, v9 offset1:1
	v_add_u32_e32 v66, 0x4040, v153
	ds_write2_b32 v66, v10, v11 offset1:1
	v_add_u32_e32 v66, 0x4048, v153
	ds_write2_b32 v66, v12, v13 offset1:1
	v_add_u32_e32 v66, 0x6060, v153
	ds_write2_b32 v66, v14, v15 offset1:1
	v_add_u32_e32 v66, 0x6068, v153
	ds_write2_b32 v66, v16, v17 offset1:1
	v_add_u32_e32 v66, 0x8080, v153
	ds_write2_b32 v66, v22, v23 offset1:1
	v_add_u32_e32 v66, 0x8088, v153
	s_add_i32 s4, s15, -1
	ds_write2_b32 v66, v24, v25 offset1:1
	v_add_u32_e32 v66, 0xa0a0, v153
	s_lshr_b32 s4, s4, 3
	ds_write2_b32 v66, v30, v31 offset1:1
	v_add_u32_e32 v66, 0xa0a8, v153
	s_mul_i32 s17, s4, s90
	ds_write2_b32 v66, v32, v33 offset1:1
	v_add_u32_e32 v66, 0xc0c0, v153
	s_add_i32 s17, s17, s12
	ds_write2_b32 v66, v38, v39 offset1:1
	v_add_u32_e32 v66, 0xc0c8, v153
	s_cmpk_gt_i32 s17, 0x7f
	ds_write2_b32 v66, v40, v41 offset1:1
	v_add_u32_e32 v66, 0xe0e0, v153
	s_cselect_b64 s[4:5], -1, 0
	ds_write2_b32 v66, v46, v47 offset1:1
	v_add_u32_e32 v66, 0xe0e8, v153
	s_and_b64 vcc, exec, s[4:5]
	ds_write2_b32 v66, v48, v49 offset1:1
	s_waitcnt lgkmcnt(0)
	s_barrier
	s_mov_b64 s[100:101], vcc
	s_cbranch_vccnz .LBB0_277
	s_sub_i32 s6, s16, 64
	s_and_b32 s7, s6, 0x180
	s_lshl_b32 s6, s17, 9
	s_and_b32 s18, s6, 0x600
	s_lshl_b32 s6, s17, 6
	s_or_b32 s7, s18, s7
	s_and_b32 s6, s6, 0xffffff00
	v_add_u32_e32 v2, s7, v146
	s_ashr_i32 s7, s6, 31
	v_ashrrev_i32_e32 v3, 31, v2
	v_lshl_add_u64 v[4:5], s[6:7], 2, v[114:115]
	v_lshlrev_b64 v[2:3], 15, v[2:3]
	v_lshl_add_u64 v[38:39], v[4:5], 0, v[2:3]
	v_add_co_u32_e32 v6, vcc, s83, v38
	s_nop 1
	v_addc_co_u32_e32 v7, vcc, 0, v39, vcc
	v_add_co_u32_e32 v10, vcc, s23, v38
	v_addc_co_u32_e32 v11, vcc, 0, v39, vcc
	v_add_co_u32_e32 v14, vcc, s24, v38
	s_nop 1
	v_addc_co_u32_e32 v15, vcc, 0, v39, vcc
	v_add_co_u32_e32 v22, vcc, s22, v38
	v_addc_co_u32_e32 v23, vcc, 0, v39, vcc
	v_add_co_u32_e32 v30, vcc, s25, v38
	s_nop 1
	v_addc_co_u32_e32 v31, vcc, 0, v39, vcc
	v_add_co_u32_e32 v40, vcc, s26, v38
	v_addc_co_u32_e32 v41, vcc, 0, v39, vcc
	v_add_co_u32_e32 v46, vcc, s27, v38
	s_nop 1
	v_addc_co_u32_e32 v47, vcc, 0, v39, vcc
.LBB0_277:
	s_add_i32 s6, s16, 0xffffff40
	s_lshl_b32 s7, s2, 9
	s_lshl_b32 s2, s2, 6
	s_and_b32 s6, s6, 0x180
	s_and_b32 s18, s7, 0x600
	s_and_b32 s2, s2, 0xffffff00
	s_or_b32 s19, s6, s18
	v_add_u32_e32 v120, s2, v147
	s_lshl_b32 s2, s19, 1
	s_add_u32 s6, s8, s2
	s_addc_u32 s7, s9, 0
	s_lshl_b32 s2, s19, 2
	v_add_u32_e32 v66, v148, v151
	v_lshl_add_u64 v[102:103], v[116:117], 0, s[2:3]
	ds_read_b32 v128, v66
	ds_read_b32 v129, v66 offset:1028
	ds_read_b32 v130, v66 offset:2056
	ds_read_b32 v131, v66 offset:3084
	ds_read_b32 v132, v66 offset:4112
	ds_read_b32 v133, v66 offset:5140
	ds_read_b32 v134, v66 offset:6168
	ds_read_b32 v135, v66 offset:7196
	global_load_dwordx4 v[70:73], v[102:103], off offset:16
	global_load_dwordx4 v[78:81], v[102:103], off
	v_ashrrev_i32_e32 v121, 31, v120
	v_lshlrev_b64 v[124:125], 12, v[120:121]
	v_lshl_add_u64 v[82:83], s[6:7], 0, v[124:125]
	v_lshl_add_u64 v[106:107], v[118:119], 0, s[2:3]
	v_lshl_add_u64 v[126:127], v[82:83], 0, v[0:1]
	global_load_dwordx4 v[66:69], v[106:107], off offset:16
	global_load_dwordx4 v[74:77], v[106:107], off
	global_load_dwordx4 v[186:189], v[102:103], off offset:80
	global_load_dwordx4 v[190:193], v[102:103], off offset:64
	global_load_dwordx4 v[194:197], v[106:107], off offset:80
	global_load_dwordx4 v[198:201], v[106:107], off offset:64
	global_load_dwordx4 v[212:215], v[102:103], off offset:144
	global_load_dwordx4 v[216:219], v[102:103], off offset:128
	global_load_dwordx4 v[220:223], v[106:107], off offset:144
	global_load_dwordx4 v[224:227], v[106:107], off offset:128
	global_load_dwordx4 v[228:231], v[102:103], off offset:208
	global_load_dwordx4 v[232:235], v[102:103], off offset:192
	global_load_dwordx4 v[236:239], v[106:107], off offset:208
	global_load_dwordx4 v[240:243], v[106:107], off offset:192
	s_mov_b64 vcc, s[100:101]
	s_cbranch_vccnz .Lfold_skip_p5A
	global_load_dwordx4 v[2:5], v[38:39], off nt
	global_load_dwordx4 v[6:9], v[6:7], off nt
	global_load_dwordx4 v[10:13], v[10:11], off nt
	global_load_dwordx4 v[14:17], v[14:15], off nt
	global_load_dwordx4 v[22:25], v[22:23], off nt
	global_load_dwordx4 v[30:33], v[30:31], off nt
	global_load_dwordx4 v[38:41], v[40:41], off nt
	global_load_dwordx4 v[46:49], v[46:47], off nt
	s_waitcnt vmcnt(8)
	s_branch .Lfold_join_p5A

.Lfold_join_p5A:
	v_add_u32_e32 v104, v148, v152
	s_lshr_b32 s2, s15, 3
	s_mul_i32 s2, s2, s90
	s_add_i32 s2, s2, s12
	s_cmpk_gt_i32 s2, 0x7f
	s_waitcnt lgkmcnt(0)
	v_mul_f32_e32 v73, v135, v73
	v_mul_f32_e32 v78, v128, v78
	v_mul_f32_e32 v79, v129, v79
	v_mul_f32_e32 v80, v130, v80
	v_mul_f32_e32 v81, v131, v81
	v_mul_f32_e32 v84, v132, v70
	v_mul_f32_e32 v85, v133, v71
	v_mul_f32_e32 v86, v134, v72
	v_cvt_pk_bf16_f32 v70, v78, v79
	v_cvt_pk_bf16_f32 v71, v80, v81
	v_cvt_pk_bf16_f32 v72, v84, v85
	v_cvt_pk_bf16_f32 v73, v86, v73
	flat_store_dwordx4 v[126:127], v[70:73]
	ds_read_b32 v136, v104
	ds_read_b32 v137, v104 offset:1028
	ds_read_b32 v138, v104 offset:2056
	ds_read_b32 v139, v104 offset:3084
	ds_read_b32 v140, v104 offset:4112
	ds_read_b32 v141, v104 offset:5140
	ds_read_b32 v142, v104 offset:6168
	ds_read_b32 v143, v104 offset:7196
	s_waitcnt lgkmcnt(0)
	v_mov_b32_e32 v82, v186
	v_mov_b32_e32 v83, v187
	v_mov_b32_e32 v84, v188
	v_mov_b32_e32 v85, v189
	v_mov_b32_e32 v90, v190
	v_mov_b32_e32 v91, v191
	v_mov_b32_e32 v92, v192
	v_mov_b32_e32 v93, v193
	v_mov_b32_e32 v78, v194
	v_mov_b32_e32 v79, v195
	v_mov_b32_e32 v80, v196
	v_mov_b32_e32 v81, v197
	v_mov_b32_e32 v86, v198
	v_mov_b32_e32 v87, v199
	v_mov_b32_e32 v88, v200
	v_mov_b32_e32 v89, v201
	v_mul_f32_e32 v85, v143, v85
	v_mul_f32_e32 v90, v136, v90
	v_mul_f32_e32 v91, v137, v91
	v_mul_f32_e32 v92, v138, v92
	v_mul_f32_e32 v93, v139, v93
	v_mul_f32_e32 v94, v140, v82
	v_mul_f32_e32 v95, v141, v83
	v_mul_f32_e32 v96, v142, v84
	v_cvt_pk_bf16_f32 v82, v90, v91
	v_cvt_pk_bf16_f32 v83, v92, v93
	v_cvt_pk_bf16_f32 v84, v94, v95
	v_cvt_pk_bf16_f32 v85, v96, v85
	flat_store_dwordx4 v[126:127], v[82:85] offset:32
	ds_read_b32 v144, v104 offset:16448
	ds_read_b32 v145, v104 offset:17476
	ds_read_b32 v155, v104 offset:18504
	ds_read_b32 v156, v104 offset:19532
	ds_read_b32 v157, v104 offset:20560
	ds_read_b32 v158, v104 offset:21588
	ds_read_b32 v159, v104 offset:22616
	ds_read_b32 v160, v104 offset:23644
	s_waitcnt lgkmcnt(0)
	v_mov_b32_e32 v94, v212
	v_mov_b32_e32 v95, v213
	v_mov_b32_e32 v96, v214
	v_mov_b32_e32 v97, v215
	v_mov_b32_e32 v108, v216
	v_mov_b32_e32 v109, v217
	v_mov_b32_e32 v110, v218
	v_mov_b32_e32 v111, v219
	v_mov_b32_e32 v90, v220
	v_mov_b32_e32 v91, v221
	v_mov_b32_e32 v92, v222
	v_mov_b32_e32 v93, v223
	v_mov_b32_e32 v98, v224
	v_mov_b32_e32 v99, v225
	v_mov_b32_e32 v100, v226
	v_mov_b32_e32 v101, v227
	v_mul_f32_e32 v97, v160, v97
	v_mul_f32_e32 v105, v144, v108
	v_mul_f32_e32 v108, v145, v109
	v_mul_f32_e32 v109, v155, v110
	v_mul_f32_e32 v110, v156, v111
	v_mul_f32_e32 v111, v157, v94
	v_mul_f32_e32 v112, v158, v95
	v_mul_f32_e32 v113, v159, v96
	v_cvt_pk_bf16_f32 v94, v105, v108
	v_cvt_pk_bf16_f32 v95, v109, v110
	v_cvt_pk_bf16_f32 v96, v111, v112
	v_cvt_pk_bf16_f32 v97, v113, v97
	flat_store_dwordx4 v[126:127], v[94:97] offset:64
	ds_read_b32 v161, v104 offset:32896
	ds_read_b32 v162, v104 offset:33924
	ds_read_b32 v163, v104 offset:34952
	ds_read_b32 v164, v104 offset:35980
	ds_read_b32 v165, v104 offset:37008
	ds_read_b32 v166, v104 offset:38036
	ds_read_b32 v167, v104 offset:39064
	ds_read_b32 v168, v104 offset:40092
	s_nop 0
	s_waitcnt lgkmcnt(0)
	v_mov_b32_e32 v178, v228
	v_mov_b32_e32 v179, v229
	v_mov_b32_e32 v180, v230
	v_mov_b32_e32 v181, v231
	v_mov_b32_e32 v182, v232
	v_mov_b32_e32 v183, v233
	v_mov_b32_e32 v184, v234
	v_mov_b32_e32 v185, v235
	v_mov_b32_e32 v102, v236
	v_mov_b32_e32 v103, v237
	v_mov_b32_e32 v104, v238
	v_mov_b32_e32 v105, v239
	v_mov_b32_e32 v110, v240
	v_mov_b32_e32 v111, v241
	v_mov_b32_e32 v112, v242
	v_mov_b32_e32 v113, v243
	v_mul_f32_e32 v169, v165, v178
	v_mul_f32_e32 v106, v161, v182
	v_mul_f32_e32 v107, v162, v183
	v_mul_f32_e32 v108, v163, v184
	v_mul_f32_e32 v109, v164, v185
	v_mul_f32_e32 v172, v166, v179
	v_mul_f32_e32 v173, v167, v180
	v_mul_f32_e32 v174, v168, v181
	v_cvt_pk_bf16_f32 v106, v106, v107
	v_cvt_pk_bf16_f32 v107, v108, v109
	v_cvt_pk_bf16_f32 v108, v169, v172
	v_cvt_pk_bf16_f32 v109, v173, v174
	flat_store_dwordx4 v[126:127], v[106:109] offset:96
	v_add_u32_e32 v126, 0x2020, v154
	ds_write2_b32 v154, v18, v19 offset1:1
	ds_write2_b32 v154, v20, v21 offset0:2 offset1:3
	ds_write2_b32 v126, v26, v27 offset1:1
	v_add_u32_e32 v126, 0x2028, v154
	ds_write2_b32 v126, v28, v29 offset1:1
	v_add_u32_e32 v126, 0x4040, v154
	ds_write2_b32 v126, v34, v35 offset1:1
	v_add_u32_e32 v126, 0x4048, v154
	ds_write2_b32 v126, v36, v37 offset1:1
	v_add_u32_e32 v126, 0x6060, v154
	ds_write2_b32 v126, v42, v43 offset1:1
	v_add_u32_e32 v126, 0x6068, v154
	ds_write2_b32 v126, v44, v45 offset1:1
	v_add_u32_e32 v126, 0x8080, v154
	ds_write2_b32 v126, v50, v51 offset1:1
	v_add_u32_e32 v126, 0x8088, v154
	ds_write2_b32 v126, v52, v53 offset1:1
	v_add_u32_e32 v126, 0xa0a0, v154
	ds_write2_b32 v126, v54, v55 offset1:1
	v_add_u32_e32 v126, 0xa0a8, v154
	ds_write2_b32 v126, v56, v57 offset1:1
	v_add_u32_e32 v126, 0xc0c0, v154
	ds_write2_b32 v126, v58, v59 offset1:1
	v_add_u32_e32 v126, 0xc0c8, v154
	ds_write2_b32 v126, v60, v61 offset1:1
	v_add_u32_e32 v126, 0xe0e0, v154
	ds_write2_b32 v126, v62, v63 offset1:1
	v_add_u32_e32 v126, 0xe0e8, v154
	ds_write2_b32 v126, v64, v65 offset1:1
	s_waitcnt lgkmcnt(0)
	s_barrier
	s_cselect_b64 s[100:101], -1, 0
	s_cbranch_scc1 .LBB0_279
	s_lshl_b32 s6, s2, 9
	s_and_b32 s7, s16, 0x1c0
	s_and_b32 s19, s6, 0x600
	s_lshl_b32 s2, s2, 6
	s_and_b32 s6, s2, 0xffffff00
	s_or_b32 s2, s19, s7
	v_add_u32_e32 v18, s2, v146
	s_ashr_i32 s7, s6, 31
	v_ashrrev_i32_e32 v19, 31, v18
	v_lshl_add_u64 v[20:21], s[6:7], 2, v[114:115]
	v_lshlrev_b64 v[18:19], 15, v[18:19]
	v_lshl_add_u64 v[58:59], v[20:21], 0, v[18:19]
	v_add_co_u32_e32 v26, vcc, 0x40000, v58
	s_nop 1
	v_addc_co_u32_e32 v27, vcc, 0, v59, vcc
	v_add_co_u32_e32 v34, vcc, 0x80000, v58
	v_addc_co_u32_e32 v35, vcc, 0, v59, vcc
	v_add_co_u32_e32 v42, vcc, 0xc0000, v58
	s_nop 1
	v_addc_co_u32_e32 v43, vcc, 0, v59, vcc
	v_add_co_u32_e32 v50, vcc, 0x100000, v58
	v_addc_co_u32_e32 v51, vcc, 0, v59, vcc
	v_add_co_u32_e32 v54, vcc, 0x140000, v58
	s_nop 1
	v_addc_co_u32_e32 v55, vcc, 0, v59, vcc
	v_add_co_u32_e32 v60, vcc, 0x180000, v58
	v_addc_co_u32_e32 v61, vcc, 0, v59, vcc
	v_add_co_u32_e32 v62, vcc, 0x1c0000, v58
	s_nop 1
	v_addc_co_u32_e32 v63, vcc, 0, v59, vcc
.LBB0_279:
	v_mul_f32_e32 v74, v128, v74
	v_mul_f32_e32 v126, v129, v75
	v_mul_f32_e32 v66, v132, v66
	v_mul_f32_e32 v128, v133, v67
	v_mul_f32_e32 v68, v134, v68
	v_mul_f32_e32 v132, v135, v69
	v_lshlrev_b32_e32 v67, 16, v72
	v_and_b32_e32 v129, 0xffff0000, v72
	v_lshlrev_b32_e32 v69, 16, v73
	v_and_b32_e32 v133, 0xffff0000, v73
	v_mul_f32_e32 v76, v130, v76
	v_mul_f32_e32 v130, v131, v77
	v_lshlrev_b32_e32 v75, 16, v70
	v_and_b32_e32 v127, 0xffff0000, v70
	v_lshlrev_b32_e32 v77, 16, v71
	v_and_b32_e32 v131, 0xffff0000, v71
	v_mul_f32_e32 v70, v136, v86
	v_mul_f32_e32 v134, v137, v87
	v_mul_f32_e32 v86, v138, v88
	v_mul_f32_e32 v136, v139, v89
	v_lshlrev_b32_e32 v71, 16, v82
	v_and_b32_e32 v135, 0xffff0000, v82
	v_lshlrev_b32_e32 v87, 16, v83
	v_and_b32_e32 v137, 0xffff0000, v83
	v_pk_add_f32 v[66:67], v[66:67], v[128:129]
	v_pk_add_f32 v[68:69], v[68:69], v[132:133]
	v_mul_f32_e32 v72, v140, v78
	v_mul_f32_e32 v88, v141, v79
	v_mul_f32_e32 v78, v142, v80
	v_mul_f32_e32 v80, v143, v81
	v_lshlrev_b32_e32 v73, 16, v84
	v_and_b32_e32 v89, 0xffff0000, v84
	v_lshlrev_b32_e32 v79, 16, v85
	v_and_b32_e32 v81, 0xffff0000, v85
	v_pk_add_f32 v[66:67], v[66:67], v[68:69]
	v_pk_add_f32 v[68:69], v[70:71], v[134:135]
	v_pk_add_f32 v[70:71], v[86:87], v[136:137]
	v_mul_f32_e32 v82, v144, v98
	v_pk_add_f32 v[68:69], v[68:69], v[70:71]
	v_pk_add_f32 v[70:71], v[72:73], v[88:89]
	v_pk_add_f32 v[72:73], v[78:79], v[80:81]
	v_mul_f32_e32 v138, v145, v99
	v_mul_f32_e32 v98, v155, v100
	v_mul_f32_e32 v140, v156, v101
	v_lshlrev_b32_e32 v83, 16, v94
	v_and_b32_e32 v139, 0xffff0000, v94
	v_lshlrev_b32_e32 v99, 16, v95
	v_and_b32_e32 v141, 0xffff0000, v95
	v_pk_add_f32 v[74:75], v[74:75], v[126:127]
	v_pk_add_f32 v[76:77], v[76:77], v[130:131]
	v_pk_add_f32 v[70:71], v[70:71], v[72:73]
	v_mul_f32_e32 v84, v157, v90
	v_mul_f32_e32 v100, v158, v91
	v_mul_f32_e32 v90, v159, v92
	v_mul_f32_e32 v92, v160, v93
	v_lshlrev_b32_e32 v85, 16, v96
	v_and_b32_e32 v101, 0xffff0000, v96
	v_lshlrev_b32_e32 v91, 16, v97
	v_and_b32_e32 v93, 0xffff0000, v97
	v_pk_add_f32 v[74:75], v[74:75], v[76:77]
	v_pk_add_f32 v[68:69], v[68:69], v[70:71]
	v_pk_add_f32 v[70:71], v[82:83], v[138:139]
	v_pk_add_f32 v[72:73], v[98:99], v[140:141]
	v_pk_add_f32 v[66:67], v[74:75], v[66:67]
	v_pk_add_f32 v[70:71], v[70:71], v[72:73]
	v_pk_add_f32 v[72:73], v[84:85], v[100:101]
	v_pk_add_f32 v[74:75], v[90:91], v[92:93]
	s_add_i32 s2, s15, -3
	v_mul_f32_e32 v94, v161, v110
	v_mul_f32_e32 v142, v162, v111
	v_mul_f32_e32 v110, v163, v112
	v_mul_f32_e32 v144, v164, v113
	v_lshlrev_b32_e32 v95, 16, v106
	v_and_b32_e32 v143, 0xffff0000, v106
	v_lshlrev_b32_e32 v111, 16, v107
	v_and_b32_e32 v145, 0xffff0000, v107
	v_pk_add_f32 v[72:73], v[72:73], v[74:75]
	v_mul_f32_e32 v96, v165, v102
	v_mul_f32_e32 v112, v166, v103
	v_mul_f32_e32 v102, v167, v104
	v_mul_f32_e32 v104, v168, v105
	v_lshlrev_b32_e32 v97, 16, v108
	v_and_b32_e32 v113, 0xffff0000, v108
	v_lshlrev_b32_e32 v103, 16, v109
	v_and_b32_e32 v105, 0xffff0000, v109
	s_and_b32 s6, s2, 6
	v_pk_add_f32 v[70:71], v[70:71], v[72:73]
	v_pk_add_f32 v[72:73], v[94:95], v[142:143]
	v_pk_add_f32 v[74:75], v[110:111], v[144:145]
	s_lshl_b32 s2, s6, 6
	v_pk_add_f32 v[72:73], v[72:73], v[74:75]
	v_pk_add_f32 v[74:75], v[96:97], v[112:113]
	v_pk_add_f32 v[76:77], v[102:103], v[104:105]
	v_pk_add_f32 v[66:67], v[122:123], v[66:67]
	v_pk_add_f32 v[74:75], v[74:75], v[76:77]
	v_pk_add_f32 v[66:67], v[66:67], v[68:69]
	s_or_b32 s7, s2, s18
	v_pk_add_f32 v[72:73], v[72:73], v[74:75]
	v_pk_add_f32 v[66:67], v[66:67], v[70:71]
	s_lshl_b32 s20, s7, 2
	s_mov_b32 s21, s3
	v_pk_add_f32 v[74:75], v[66:67], v[72:73]
	v_add_u32_e32 v66, v149, v151
	v_lshl_add_u64 v[110:111], v[116:117], 0, s[20:21]
	v_lshl_add_u64 v[92:93], v[118:119], 0, s[20:21]
	ds_read_b32 v85, v66
	ds_read_b32 v87, v66 offset:1028
	ds_read_b32 v89, v66 offset:2056
	ds_read_b32 v91, v66 offset:3084
	ds_read_b32 v98, v66 offset:4112
	ds_read_b32 v99, v66 offset:5140
	ds_read_b32 v100, v66 offset:6168
	ds_read_b32 v101, v66 offset:7196
	global_load_dwordx4 v[66:69], v[110:111], off offset:272
	global_load_dwordx4 v[94:97], v[110:111], off offset:256
	global_load_dwordx4 v[76:79], v[92:93], off offset:272
	global_load_dwordx4 v[80:83], v[92:93], off offset:256
	global_load_dwordx4 v[186:189], v[110:111], off offset:336
	global_load_dwordx4 v[190:193], v[110:111], off offset:320
	global_load_dwordx4 v[194:197], v[92:93], off offset:336
	global_load_dwordx4 v[198:201], v[92:93], off offset:320
	global_load_dwordx4 v[212:215], v[110:111], off offset:400
	global_load_dwordx4 v[216:219], v[110:111], off offset:384
	global_load_dwordx4 v[220:223], v[92:93], off offset:400
	global_load_dwordx4 v[224:227], v[92:93], off offset:384
	global_load_dwordx4 v[228:231], v[110:111], off offset:464
	global_load_dwordx4 v[232:235], v[110:111], off offset:448
	global_load_dwordx4 v[236:239], v[92:93], off offset:464
	global_load_dwordx4 v[240:243], v[92:93], off offset:448
	s_mov_b64 vcc, s[100:101]
	s_cbranch_vccnz .Lfold_skip_p5B
	global_load_dwordx4 v[18:21], v[58:59], off nt
	global_load_dwordx4 v[26:29], v[26:27], off nt
	global_load_dwordx4 v[34:37], v[34:35], off nt
	global_load_dwordx4 v[42:45], v[42:43], off nt
	global_load_dwordx4 v[50:53], v[50:51], off nt
	global_load_dwordx4 v[54:57], v[54:55], off nt
	global_load_dwordx4 v[58:61], v[60:61], off nt
	global_load_dwordx4 v[62:65], v[62:63], off nt
	s_waitcnt vmcnt(8)
	s_branch .Lfold_join_p5B

.Lfold_join_p5B:
	s_lshl_b32 s2, s7, 1
	v_lshl_add_u64 v[72:73], s[8:9], 0, v[124:125]
	s_bitset1_b32 s2, 7
	v_lshl_add_u64 v[70:71], v[72:73], 0, s[2:3]
	v_lshl_add_u64 v[72:73], v[72:73], 0, v[0:1]
	v_lshl_add_u64 v[72:73], v[72:73], 0, s[2:3]
	v_add_u32_e32 v138, v149, v152
	v_lshl_add_u64 v[134:135], v[70:71], 0, v[0:1]
	s_cmp_lg_u32 s6, 6
	s_waitcnt lgkmcnt(0)
	v_mul_f32_e32 v69, v101, v69
	v_mul_f32_e32 v88, v85, v80
	v_mul_f32_e32 v90, v87, v81
	v_mul_f32_e32 v84, v89, v82
	v_mul_f32_e32 v86, v91, v83
	v_mul_f32_e32 v80, v98, v76
	v_mul_f32_e32 v82, v99, v77
	v_mul_f32_e32 v76, v100, v78
	v_mul_f32_e32 v78, v101, v79
	v_mul_f32_e32 v77, v85, v94
	v_mul_f32_e32 v79, v87, v95
	v_mul_f32_e32 v81, v89, v96
	v_mul_f32_e32 v83, v91, v97
	v_mul_f32_e32 v85, v98, v66
	v_mul_f32_e32 v87, v99, v67
	v_mul_f32_e32 v89, v100, v68
	v_cvt_pk_bf16_f32 v66, v77, v79
	v_cvt_pk_bf16_f32 v67, v81, v83
	v_cvt_pk_bf16_f32 v68, v85, v87
	v_cvt_pk_bf16_f32 v69, v89, v69
	flat_store_dwordx4 v[72:73], v[66:69]
	v_lshlrev_b32_e32 v89, 16, v66
	v_and_b32_e32 v91, 0xffff0000, v66
	v_lshlrev_b32_e32 v85, 16, v67
	v_and_b32_e32 v87, 0xffff0000, v67
	v_lshlrev_b32_e32 v81, 16, v68
	v_and_b32_e32 v83, 0xffff0000, v68
	v_lshlrev_b32_e32 v77, 16, v69
	v_and_b32_e32 v79, 0xffff0000, v69
	ds_read_b32 v72, v138
	ds_read_b32 v73, v138 offset:1028
	ds_read_b32 v103, v138 offset:2056
	ds_read_b32 v105, v138 offset:3084
	ds_read_b32 v107, v138 offset:4112
	ds_read_b32 v109, v138 offset:5140
	ds_read_b32 v112, v138 offset:6168
	ds_read_b32 v113, v138 offset:7196
	v_pk_add_f32 v[88:89], v[88:89], v[90:91]
	v_pk_add_f32 v[84:85], v[84:85], v[86:87]
	v_pk_add_f32 v[80:81], v[80:81], v[82:83]
	v_pk_add_f32 v[76:77], v[76:77], v[78:79]
	v_pk_add_f32 v[84:85], v[88:89], v[84:85]
	v_pk_add_f32 v[76:77], v[80:81], v[76:77]
	s_waitcnt lgkmcnt(0)
	v_mov_b32_e32 v66, v186
	v_mov_b32_e32 v67, v187
	v_mov_b32_e32 v68, v188
	v_mov_b32_e32 v69, v189
	v_mov_b32_e32 v122, v190
	v_mov_b32_e32 v123, v191
	v_mov_b32_e32 v124, v192
	v_mov_b32_e32 v125, v193
	v_mov_b32_e32 v94, v194
	v_mov_b32_e32 v95, v195
	v_mov_b32_e32 v96, v196
	v_mov_b32_e32 v97, v197
	v_mov_b32_e32 v98, v198
	v_mov_b32_e32 v99, v199
	v_mov_b32_e32 v100, v200
	v_mov_b32_e32 v101, v201
	v_mul_f32_e32 v69, v113, v69
	v_pk_add_f32 v[76:77], v[84:85], v[76:77]
	v_mul_f32_e32 v106, v72, v98
	v_mul_f32_e32 v108, v73, v99
	v_mul_f32_e32 v102, v103, v100
	v_mul_f32_e32 v104, v105, v101
	v_mul_f32_e32 v98, v107, v94
	v_mul_f32_e32 v100, v109, v95
	v_mul_f32_e32 v94, v112, v96
	v_mul_f32_e32 v96, v113, v97
	v_mul_f32_e32 v72, v72, v122
	v_mul_f32_e32 v73, v73, v123
	v_mul_f32_e32 v95, v103, v124
	v_mul_f32_e32 v97, v105, v125
	v_mul_f32_e32 v99, v107, v66
	v_mul_f32_e32 v101, v109, v67
	v_mul_f32_e32 v103, v112, v68
	v_cvt_pk_bf16_f32 v66, v72, v73
	v_cvt_pk_bf16_f32 v67, v95, v97
	v_cvt_pk_bf16_f32 v68, v99, v101
	v_cvt_pk_bf16_f32 v69, v103, v69
	flat_store_dwordx4 v[134:135], v[66:69] offset:32
	v_lshlrev_b32_e32 v107, 16, v66
	v_and_b32_e32 v109, 0xffff0000, v66
	v_lshlrev_b32_e32 v103, 16, v67
	v_and_b32_e32 v105, 0xffff0000, v67
	v_lshlrev_b32_e32 v99, 16, v68
	v_and_b32_e32 v101, 0xffff0000, v68
	v_lshlrev_b32_e32 v95, 16, v69
	v_and_b32_e32 v97, 0xffff0000, v69
	ds_read_b32 v113, v138 offset:16448
	ds_read_b32 v127, v138 offset:17476
	ds_read_b32 v129, v138 offset:18504
	ds_read_b32 v131, v138 offset:19532
	ds_read_b32 v133, v138 offset:20560
	ds_read_b32 v137, v138 offset:21588
	ds_read_b32 v139, v138 offset:22616
	ds_read_b32 v144, v138 offset:23644
	v_pk_add_f32 v[74:75], v[74:75], v[76:77]
	v_pk_add_f32 v[76:77], v[106:107], v[108:109]
	v_pk_add_f32 v[78:79], v[102:103], v[104:105]
	v_pk_add_f32 v[80:81], v[94:95], v[96:97]
	v_pk_add_f32 v[76:77], v[76:77], v[78:79]
	v_pk_add_f32 v[78:79], v[98:99], v[100:101]
	s_waitcnt lgkmcnt(0)
	v_mov_b32_e32 v66, v212
	v_mov_b32_e32 v67, v213
	v_mov_b32_e32 v68, v214
	v_mov_b32_e32 v69, v215
	v_mov_b32_e32 v70, v216
	v_mov_b32_e32 v71, v217
	v_mov_b32_e32 v72, v218
	v_mov_b32_e32 v73, v219
	v_mov_b32_e32 v140, v220
	v_mov_b32_e32 v141, v221
	v_mov_b32_e32 v142, v222
	v_mov_b32_e32 v143, v223
	v_mov_b32_e32 v122, v224
	v_mov_b32_e32 v123, v225
	v_mov_b32_e32 v124, v226
	v_mov_b32_e32 v125, v227
	v_mul_f32_e32 v69, v144, v69
	v_mul_f32_e32 v70, v113, v70
	v_mul_f32_e32 v71, v127, v71
	v_mul_f32_e32 v132, v113, v122
	v_mul_f32_e32 v136, v127, v123
	v_mul_f32_e32 v130, v131, v125
	v_mul_f32_e32 v72, v129, v72
	v_mul_f32_e32 v73, v131, v73
	v_mul_f32_e32 v113, v133, v66
	v_mul_f32_e32 v123, v137, v67
	v_mul_f32_e32 v125, v139, v68
	v_cvt_pk_bf16_f32 v66, v70, v71
	v_cvt_pk_bf16_f32 v67, v72, v73
	v_cvt_pk_bf16_f32 v68, v113, v123
	v_cvt_pk_bf16_f32 v69, v125, v69
	flat_store_dwordx4 v[134:135], v[66:69] offset:64
	v_mul_f32_e32 v128, v129, v124
	v_mul_f32_e32 v124, v133, v140
	v_mul_f32_e32 v126, v137, v141
	v_mul_f32_e32 v112, v139, v142
	v_mul_f32_e32 v122, v144, v143
	v_lshlrev_b32_e32 v133, 16, v66
	v_and_b32_e32 v137, 0xffff0000, v66
	v_lshlrev_b32_e32 v129, 16, v67
	v_and_b32_e32 v131, 0xffff0000, v67
	v_lshlrev_b32_e32 v125, 16, v68
	v_and_b32_e32 v127, 0xffff0000, v68
	v_lshlrev_b32_e32 v113, 16, v69
	v_and_b32_e32 v123, 0xffff0000, v69
	ds_read_b32 v139, v138 offset:32896
	ds_read_b32 v141, v138 offset:33924
	ds_read_b32 v155, v138 offset:34952
	ds_read_b32 v160, v138 offset:35980
	ds_read_b32 v161, v138 offset:37008
	ds_read_b32 v162, v138 offset:38036
	ds_read_b32 v163, v138 offset:39064
	ds_read_b32 v164, v138 offset:40092
	v_pk_add_f32 v[78:79], v[78:79], v[80:81]
	v_pk_add_f32 v[80:81], v[112:113], v[122:123]
	v_pk_add_f32 v[76:77], v[76:77], v[78:79]
	v_pk_add_f32 v[78:79], v[128:129], v[130:131]
	v_pk_add_f32 v[74:75], v[74:75], v[76:77]
	v_pk_add_f32 v[76:77], v[132:133], v[136:137]
	s_waitcnt lgkmcnt(0)
	v_mov_b32_e32 v142, v228
	v_mov_b32_e32 v143, v229
	v_mov_b32_e32 v144, v230
	v_mov_b32_e32 v145, v231
	v_mov_b32_e32 v156, v232
	v_mov_b32_e32 v157, v233
	v_mov_b32_e32 v158, v234
	v_mov_b32_e32 v159, v235
	v_mov_b32_e32 v66, v236
	v_mov_b32_e32 v67, v237
	v_mov_b32_e32 v68, v238
	v_mov_b32_e32 v69, v239
	v_mov_b32_e32 v70, v240
	v_mov_b32_e32 v71, v241
	v_mov_b32_e32 v72, v242
	v_mov_b32_e32 v73, v243
	v_mul_f32_e32 v93, v161, v142
	v_pk_add_f32 v[76:77], v[76:77], v[78:79]
	v_pk_add_f32 v[78:79], v[124:125], v[126:127]
	v_mul_f32_e32 v138, v139, v70
	v_mul_f32_e32 v140, v141, v71
	v_mul_f32_e32 v92, v155, v72
	v_mul_f32_e32 v110, v160, v73
	v_mul_f32_e32 v70, v161, v66
	v_mul_f32_e32 v72, v162, v67
	v_mul_f32_e32 v66, v163, v68
	v_mul_f32_e32 v68, v164, v69
	v_mul_f32_e32 v67, v139, v156
	v_mul_f32_e32 v69, v141, v157
	v_mul_f32_e32 v71, v155, v158
	v_mul_f32_e32 v73, v160, v159
	v_mul_f32_e32 v111, v162, v143
	v_mul_f32_e32 v139, v163, v144
	v_mul_f32_e32 v141, v164, v145
	v_pk_add_f32 v[78:79], v[78:79], v[80:81]
	v_cvt_pk_bf16_f32 v142, v67, v69
	v_cvt_pk_bf16_f32 v143, v71, v73
	v_cvt_pk_bf16_f32 v144, v93, v111
	v_cvt_pk_bf16_f32 v145, v139, v141
	flat_store_dwordx4 v[134:135], v[142:145] offset:96
	v_lshlrev_b32_e32 v139, 16, v142
	v_and_b32_e32 v141, 0xffff0000, v142
	v_lshlrev_b32_e32 v93, 16, v143
	v_and_b32_e32 v111, 0xffff0000, v143
	v_lshlrev_b32_e32 v71, 16, v144
	v_and_b32_e32 v73, 0xffff0000, v144
	v_lshlrev_b32_e32 v67, 16, v145
	v_and_b32_e32 v69, 0xffff0000, v145
	v_pk_add_f32 v[76:77], v[76:77], v[78:79]
	v_pk_add_f32 v[78:79], v[92:93], v[110:111]
	v_pk_add_f32 v[74:75], v[74:75], v[76:77]
	v_pk_add_f32 v[76:77], v[138:139], v[140:141]
	v_pk_add_f32 v[70:71], v[70:71], v[72:73]
	v_pk_add_f32 v[66:67], v[66:67], v[68:69]
	v_pk_add_f32 v[76:77], v[76:77], v[78:79]
	v_pk_add_f32 v[66:67], v[70:71], v[66:67]
	s_nop 0
	v_pk_add_f32 v[66:67], v[76:77], v[66:67]
	s_nop 0
	v_pk_add_f32 v[122:123], v[74:75], v[66:67]
	s_cbranch_scc1 .LBB0_274
	ds_bpermute_b32 v66, v150, v123
	ds_bpermute_b32 v67, v150, v122
	s_and_saveexec_b64 s[6:7], s[0:1]
	s_cbranch_execz .LBB0_273
	s_lshl_b32 s2, s18, 6
	s_add_u32 s18, s13, s2
	s_addc_u32 s19, s14, 0
	s_waitcnt lgkmcnt(0)
	v_add_f32_e32 v68, v122, v67
	v_add_f32_e32 v69, v123, v66
	v_lshl_add_u64 v[66:67], v[120:121], 2, s[18:19]
	flat_store_dword v[66:67], v69
	v_add_co_u32_e32 v66, vcc, 0x20000, v66
	s_nop 1
	v_addc_co_u32_e32 v67, vcc, 0, v67, vcc
	flat_store_dword v[66:67], v68
	s_branch .LBB0_273

; #define CW_COORD(j, valid, k0, n0) do { if (FOLD) { const int _u = u0 + ((j) >> 3) * G; valid = _u < nunits; n0 = (_u >> 2) << 8; k0 = (_u & 3) * 512 + ((j) & 7) * 64; } \
;                                         else { const int _t = bid + (j) * G; valid = _t < nt_all; k0 = (_t % ntk) << 6; n0 = (_t / ntk) << 8; } } while (0)
; #define CW_LOAD(v, j) do { bool _ok; int _k0, _n0; CW_COORD(j, _ok, _k0, _n0); if (_ok) { _Pragma("unroll") for (int i = 0; i < 8; ++i) v[i] = __builtin_nontemporal_load((const f32x4*)(W + (size_t)(_k0 + lk + 8 * i) * N + _n0 + ln4)); } } while (0)
; template <bool FOLD> ...
;     ...
;     const int G = vG, bid = vbid, ntk = K >> 6, nt_all = ntk * (N >> 8), nunits = (N >> 8) * 4, u0 = vbid;
;     const int lk = tid >> 6, ln4 = (tid & 63) << 2, n = tid >> 1, par = tid & 1;
;     float csum = 0.f, bsum = 0.f;
;     ...
;     f32x4 va[8], vb[8];
;     CW_LOAD(va, 0); CW_LOAD(vb, 1);
;     for (int j = 0;; j += 2) {
;         bool ok; int kk, nn; CW_COORD(j, ok, kk, nn); if (!ok) break;
;         CW_PROC(va, j, 0);
;         CW_PROC(vb, j + 1, 1);
;     }
.LBB0_886:
	v_readlane_b32 s0, v251, 29
	v_readlane_b32 s1, v251, 30
	s_ashr_i32 s1, s0, 31
	s_lshl_b64 s[0:1], s[0:1], 3
	s_add_u32 s10, s68, s0
	s_addc_u32 s11, s69, s1
	v_readlane_b32 s0, v251, 33
	v_readlane_b32 s1, v251, 34
	s_ashr_i32 s1, s0, 31
	s_mov_b64 s[36:37], s[0:1]
	s_lshl_b64 s[12:13], s[0:1], 22
	v_readlane_b32 s0, v250, 39
	v_readlane_b32 s2, v251, 28
	s_cmp_ge_i32 s2, s0
	s_cselect_b64 s[0:1], -1, 0
	s_cmp_lt_i32 s2, s78
	s_cselect_b64 s[6:7], -1, 0
	s_sub_i32 s2, s2, s78
	s_add_i32 s2, s2, 24
	s_and_b64 s[0:1], s[0:1], s[6:7]
	s_ashr_i32 s6, s2, 31
	s_lshr_b32 s6, s6, 29
	s_add_i32 s6, s2, s6
	s_and_b32 s6, s6, -8
	s_sub_i32 s22, s2, s6
	s_and_b64 s[0:1], s[0:1], exec
	s_cselect_b32 s16, s22, -1
	s_cmp_lt_i32 s16, 0
	s_mov_b32 s23, 0x2c000
	s_mov_b32 s28, 0x40000
	s_mov_b32 s29, 0x50000
	s_movk_i32 s30, 0x7800
	s_movk_i32 s31, 0x500
	v_readlane_b32 s33, v251, 55
	s_mov_b64 s[34:35], 0x40000
	s_cbranch_scc1 .LBB0_898
	s_load_dwordx4 s[24:27], s[10:11], 0x60
	s_load_dwordx2 s[0:1], s[10:11], 0x70
	s_lshl_b64 s[14:15], s[36:37], 13
	v_ashrrev_i32_e32 v67, 6, v210
	v_lshlrev_b32_e32 v68, 2, v210
	s_waitcnt lgkmcnt(0)
	s_add_u32 s6, s24, s14
	s_addc_u32 s7, s25, s15
	s_add_u32 s14, s26, s14
	s_addc_u32 s15, s27, s15
	s_add_u32 s17, s42, 0x2073f600
	s_addc_u32 s18, s43, 0
	s_add_u32 s0, s0, s12
	s_addc_u32 s1, s1, s13
	s_lshl_b32 s2, s16, 9
	s_and_b32 s19, s2, 0x600
	s_lshl_b32 s2, s16, 6
	s_and_b32 s2, s2, 0x7fffff00
	s_lshl_b64 s[20:21], s[2:3], 2
	v_and_b32_e32 v0, 0xfc, v68
	v_add_u32_e32 v114, s19, v67
	s_add_u32 s20, s0, s20
	s_addc_u32 s21, s1, s21
	v_lshlrev_b32_e32 v0, 2, v0
	v_ashrrev_i32_e32 v115, 31, v114
	s_waitcnt vmcnt(0)
	v_lshl_add_u64 v[2:3], s[20:21], 0, v[0:1]
	v_lshlrev_b64 v[4:5], 11, v[114:115]
	v_lshl_add_u64 v[58:59], v[2:3], 0, v[4:5]
	v_add_co_u32_e32 v6, vcc, s60, v58
	s_mov_b32 s2, 0x8000
	s_nop 0
	v_addc_co_u32_e32 v7, vcc, 0, v59, vcc
	v_add_co_u32_e32 v10, vcc, s2, v58
	s_mov_b32 s2, 0xc000
	s_nop 0
	v_addc_co_u32_e32 v11, vcc, 0, v59, vcc
	v_add_co_u32_e32 v14, vcc, s2, v58
	s_mov_b32 s2, 0x14000
	s_nop 0
	v_addc_co_u32_e32 v15, vcc, 0, v59, vcc
	v_add_co_u32_e32 v18, vcc, s59, v58
	global_load_dwordx4 v[2:5], v[58:59], off nt
	s_nop 0
	global_load_dwordx4 v[6:9], v[6:7], off nt
	v_addc_co_u32_e32 v19, vcc, 0, v59, vcc
	v_add_co_u32_e32 v20, vcc, s2, v58
	s_mov_b32 s2, 0x18000
	s_nop 0
	v_addc_co_u32_e32 v21, vcc, 0, v59, vcc
	global_load_dwordx4 v[10:13], v[10:11], off nt
	s_nop 0
	global_load_dwordx4 v[14:17], v[14:15], off nt
	s_nop 0
	global_load_dwordx4 v[26:29], v[18:19], off nt
	global_load_dwordx4 v[30:33], v[20:21], off nt
	v_add_co_u32_e32 v18, vcc, s2, v58
	s_mov_b32 s2, 0x1c000
	s_nop 0
	v_addc_co_u32_e32 v19, vcc, 0, v59, vcc
	v_add_co_u32_e32 v20, vcc, s2, v58
	s_mov_b32 s2, 0x34000
	s_nop 0
	v_addc_co_u32_e32 v21, vcc, 0, v59, vcc
	global_load_dwordx4 v[42:45], v[18:19], off nt
	global_load_dwordx4 v[46:49], v[20:21], off nt
	v_add_co_u32_e32 v18, vcc, s62, v58
	v_and_b32_e32 v69, 1, v210
	s_nop 0
	v_addc_co_u32_e32 v19, vcc, 0, v59, vcc
	v_add_co_u32_e32 v22, vcc, s66, v58
	v_lshl_add_u64 v[116:117], s[0:1], 0, v[0:1]
	s_nop 0
	v_addc_co_u32_e32 v23, vcc, 0, v59, vcc
	v_add_co_u32_e32 v34, vcc, s63, v58
	global_load_dwordx4 v[18:21], v[18:19], off nt
	s_nop 0
	global_load_dwordx4 v[22:25], v[22:23], off nt
	v_addc_co_u32_e32 v35, vcc, 0, v59, vcc
	v_add_co_u32_e32 v38, vcc, s23, v58
	v_lshlrev_b32_e32 v66, 3, v69
	s_nop 0
	v_addc_co_u32_e32 v39, vcc, 0, v59, vcc
	v_add_co_u32_e32 v50, vcc, s64, v58
	global_load_dwordx4 v[34:37], v[34:35], off nt
	s_nop 0
	global_load_dwordx4 v[38:41], v[38:39], off nt
	v_addc_co_u32_e32 v51, vcc, 0, v59, vcc
	v_add_co_u32_e32 v54, vcc, s2, v58
	s_mov_b32 s2, 0x38000
	s_nop 0
	v_addc_co_u32_e32 v55, vcc, 0, v59, vcc
	v_add_co_u32_e32 v60, vcc, s2, v58
	s_mov_b32 s2, 0x3c000
	s_nop 0
	v_addc_co_u32_e32 v61, vcc, 0, v59, vcc
	v_add_co_u32_e32 v62, vcc, s2, v58
	global_load_dwordx4 v[50:53], v[50:51], off nt
	s_nop 0
	global_load_dwordx4 v[54:57], v[54:55], off nt
	v_addc_co_u32_e32 v63, vcc, 0, v59, vcc
	global_load_dwordx4 v[58:61], v[60:61], off nt
	s_nop 0
	global_load_dwordx4 v[62:65], v[62:63], off nt
	v_readlane_b32 s0, v250, 62
	v_ashrrev_i32_e32 v115, 1, v210
	v_add_u32_e32 v70, 0, v0
	v_add_u32_e32 v72, s0, v0
	s_movk_i32 s2, 0x404
	v_or_b32_e32 v0, 16, v66
	v_lshlrev_b32_e32 v71, 2, v115
	v_mul_lo_u32 v67, v67, s2
	v_mul_u32_u24_e32 v152, 0x404, v0
	v_lshlrev_b32_e32 v0, 5, v69
	v_mov_b32_e32 v124, 0
	s_mov_b32 s19, 3
	v_add_u32_e32 v148, 0, v71
	v_add_u32_e32 v149, s0, v71
	v_bitop3_b32 v150, v68, 4, v205 bitop3:0x6c
	v_cmp_eq_u32_e64 s[0:1], 0, v69
	v_mul_u32_u24_e32 v151, 0x2020, v69
	v_lshl_add_u64 v[118:119], s[6:7], 0, v[0:1]
	v_lshl_add_u64 v[120:121], s[14:15], 0, v[0:1]
	s_movk_i32 s20, 0xc0
	v_add_u32_e32 v153, v70, v67
	v_lshlrev_b32_e32 v0, 1, v66
	v_add_u32_e32 v154, v72, v67
	v_mov_b32_e32 v125, v124
	s_waitcnt vmcnt(0)
	s_branch .LBB0_890

.LBB0_890:
	s_waitcnt lgkmcnt(0)
	v_add_u32_e32 v66, 0x2020, v153
	ds_write2_b32 v153, v2, v3 offset1:1
	ds_write2_b32 v153, v4, v5 offset0:2 offset1:3
	ds_write2_b32 v66, v6, v7 offset1:1
	v_add_u32_e32 v66, 0x2028, v153
	ds_write2_b32 v66, v8, v9 offset1:1
	v_add_u32_e32 v66, 0x4040, v153
	ds_write2_b32 v66, v10, v11 offset1:1
	v_add_u32_e32 v66, 0x4048, v153
	ds_write2_b32 v66, v12, v13 offset1:1
	v_add_u32_e32 v66, 0x6060, v153
	ds_write2_b32 v66, v14, v15 offset1:1
	v_add_u32_e32 v66, 0x6068, v153
	ds_write2_b32 v66, v16, v17 offset1:1
	v_add_u32_e32 v66, 0x8080, v153
	ds_write2_b32 v66, v26, v27 offset1:1
	v_add_u32_e32 v66, 0x8088, v153
	ds_write2_b32 v66, v28, v29 offset1:1
	v_add_u32_e32 v66, 0xa0a0, v153
	s_add_i32 s2, s19, -1
	ds_write2_b32 v66, v30, v31 offset1:1
	v_add_u32_e32 v66, 0xa0a8, v153
	s_and_b32 s21, s2, 0x7ffffff8
	ds_write2_b32 v66, v32, v33 offset1:1
	v_add_u32_e32 v66, 0xc0c0, v153
	s_add_i32 s21, s21, s16
	ds_write2_b32 v66, v42, v43 offset1:1
	v_add_u32_e32 v66, 0xc0c8, v153
	s_cmp_gt_i32 s21, 7
	ds_write2_b32 v66, v44, v45 offset1:1
	v_add_u32_e32 v66, 0xe0e0, v153
	s_cselect_b64 s[6:7], -1, 0
	ds_write2_b32 v66, v46, v47 offset1:1
	v_add_u32_e32 v66, 0xe0e8, v153
	s_and_b64 vcc, exec, s[6:7]
	ds_write2_b32 v66, v48, v49 offset1:1
	s_waitcnt lgkmcnt(0)
	s_barrier
	s_mov_b64 s[100:101], vcc
	s_cbranch_vccnz .LBB0_892
	s_sub_i32 s2, s20, 64
	s_and_b32 s14, s2, 0x180
	s_lshl_b32 s2, s21, 6
	v_add_u32_e32 v2, s14, v114
	s_and_b32 s2, s2, 0x7fffff00
	v_ashrrev_i32_e32 v3, 31, v2
	v_lshl_add_u64 v[4:5], s[2:3], 2, v[116:117]
	v_lshlrev_b64 v[2:3], 11, v[2:3]
	v_lshl_add_u64 v[42:43], v[4:5], 0, v[2:3]
	v_add_co_u32_e32 v6, vcc, 0x4000, v42
	s_mov_b32 s2, 0x14000
	s_nop 0
	v_addc_co_u32_e32 v7, vcc, 0, v43, vcc
	v_add_co_u32_e32 v10, vcc, 0x8000, v42
	v_addc_co_u32_e32 v11, vcc, 0, v43, vcc
	v_add_co_u32_e32 v14, vcc, 0xc000, v42
	s_nop 1
	v_addc_co_u32_e32 v15, vcc, 0, v43, vcc
	v_add_co_u32_e32 v26, vcc, s59, v42
	v_addc_co_u32_e32 v27, vcc, 0, v43, vcc
	v_add_co_u32_e32 v30, vcc, s2, v42
	s_mov_b32 s2, 0x18000
	s_nop 0
	v_addc_co_u32_e32 v31, vcc, 0, v43, vcc
	v_add_co_u32_e32 v44, vcc, s2, v42
	s_mov_b32 s2, 0x1c000
	s_nop 0
	v_addc_co_u32_e32 v45, vcc, 0, v43, vcc
	v_add_co_u32_e32 v46, vcc, s2, v42
	v_addc_co_u32_e32 v47, vcc, 0, v43, vcc
.LBB0_892:
	s_add_i32 s2, s20, 0xffffff40
	s_lshl_b32 s14, s22, 9
	s_lshl_b32 s15, s22, 6
	s_and_b32 s2, s2, 0x180
	s_and_b32 s22, s14, 0x600
	s_or_b32 s2, s2, s22
	s_and_b32 s15, s15, 0x7fffff00
	s_lshl_b32 s14, s2, 1
	v_readlane_b32 s24, v251, 37
	v_readlane_b32 s25, v251, 38
	s_add_u32 s14, s24, s14
	v_add_u32_e32 v122, s15, v115
	s_addc_u32 s15, s25, 0
	s_lshl_b32 s2, s2, 2
	v_add_u32_e32 v66, v148, v151
	v_lshl_add_u64 v[102:103], v[118:119], 0, s[2:3]
	ds_read_b32 v130, v66
	ds_read_b32 v131, v66 offset:1028
	ds_read_b32 v132, v66 offset:2056
	ds_read_b32 v133, v66 offset:3084
	ds_read_b32 v134, v66 offset:4112
	ds_read_b32 v135, v66 offset:5140
	ds_read_b32 v136, v66 offset:6168
	ds_read_b32 v137, v66 offset:7196
	global_load_dwordx4 v[70:73], v[102:103], off offset:16
	global_load_dwordx4 v[78:81], v[102:103], off
	v_ashrrev_i32_e32 v123, 31, v122
	v_lshlrev_b64 v[126:127], 12, v[122:123]
	v_lshl_add_u64 v[82:83], s[14:15], 0, v[126:127]
	v_lshl_add_u64 v[106:107], v[120:121], 0, s[2:3]
	v_lshl_add_u64 v[128:129], v[82:83], 0, v[0:1]
	global_load_dwordx4 v[66:69], v[106:107], off offset:16
	global_load_dwordx4 v[74:77], v[106:107], off
	global_load_dwordx4 v[186:189], v[102:103], off offset:80
	global_load_dwordx4 v[190:193], v[102:103], off offset:64
	global_load_dwordx4 v[194:197], v[106:107], off offset:80
	global_load_dwordx4 v[198:201], v[106:107], off offset:64
	global_load_dwordx4 v[212:215], v[102:103], off offset:144
	global_load_dwordx4 v[216:219], v[102:103], off offset:128
	global_load_dwordx4 v[220:223], v[106:107], off offset:144
	global_load_dwordx4 v[224:227], v[106:107], off offset:128
	global_load_dwordx4 v[228:231], v[102:103], off offset:208
	global_load_dwordx4 v[232:235], v[102:103], off offset:192
	global_load_dwordx4 v[236:239], v[106:107], off offset:208
	global_load_dwordx4 v[240:243], v[106:107], off offset:192
	s_mov_b64 vcc, s[100:101]
	s_cbranch_vccnz .Lfold_skip_f1A
	global_load_dwordx4 v[2:5], v[42:43], off nt
	global_load_dwordx4 v[6:9], v[6:7], off nt
	global_load_dwordx4 v[10:13], v[10:11], off nt
	global_load_dwordx4 v[14:17], v[14:15], off nt
	global_load_dwordx4 v[26:29], v[26:27], off nt
	global_load_dwordx4 v[30:33], v[30:31], off nt
	global_load_dwordx4 v[42:45], v[44:45], off nt
	global_load_dwordx4 v[46:49], v[46:47], off nt
	s_waitcnt vmcnt(8)
	s_branch .Lfold_join_f1A

.Lfold_join_f1A:
	v_add_u32_e32 v104, v148, v152
	s_and_b32 s2, s19, 0x7ffffff8
	s_add_i32 s2, s2, s16
	s_cmp_gt_i32 s2, 7
	s_waitcnt lgkmcnt(0)
	v_mul_f32_e32 v73, v137, v73
	v_mul_f32_e32 v78, v130, v78
	v_mul_f32_e32 v79, v131, v79
	v_mul_f32_e32 v80, v132, v80
	v_mul_f32_e32 v81, v133, v81
	v_mul_f32_e32 v84, v134, v70
	v_mul_f32_e32 v85, v135, v71
	v_mul_f32_e32 v86, v136, v72
	v_cvt_pk_bf16_f32 v70, v78, v79
	v_cvt_pk_bf16_f32 v71, v80, v81
	v_cvt_pk_bf16_f32 v72, v84, v85
	v_cvt_pk_bf16_f32 v73, v86, v73
	flat_store_dwordx4 v[128:129], v[70:73]
	ds_read_b32 v138, v104
	ds_read_b32 v139, v104 offset:1028
	ds_read_b32 v140, v104 offset:2056
	ds_read_b32 v141, v104 offset:3084
	ds_read_b32 v142, v104 offset:4112
	ds_read_b32 v143, v104 offset:5140
	ds_read_b32 v144, v104 offset:6168
	ds_read_b32 v145, v104 offset:7196
	s_waitcnt lgkmcnt(0)
	v_mov_b32_e32 v82, v186
	v_mov_b32_e32 v83, v187
	v_mov_b32_e32 v84, v188
	v_mov_b32_e32 v85, v189
	v_mov_b32_e32 v90, v190
	v_mov_b32_e32 v91, v191
	v_mov_b32_e32 v92, v192
	v_mov_b32_e32 v93, v193
	v_mov_b32_e32 v78, v194
	v_mov_b32_e32 v79, v195
	v_mov_b32_e32 v80, v196
	v_mov_b32_e32 v81, v197
	v_mov_b32_e32 v86, v198
	v_mov_b32_e32 v87, v199
	v_mov_b32_e32 v88, v200
	v_mov_b32_e32 v89, v201
	v_mul_f32_e32 v85, v145, v85
	v_mul_f32_e32 v90, v138, v90
	v_mul_f32_e32 v91, v139, v91
	v_mul_f32_e32 v92, v140, v92
	v_mul_f32_e32 v93, v141, v93
	v_mul_f32_e32 v94, v142, v82
	v_mul_f32_e32 v95, v143, v83
	v_mul_f32_e32 v96, v144, v84
	v_cvt_pk_bf16_f32 v82, v90, v91
	v_cvt_pk_bf16_f32 v83, v92, v93
	v_cvt_pk_bf16_f32 v84, v94, v95
	v_cvt_pk_bf16_f32 v85, v96, v85
	flat_store_dwordx4 v[128:129], v[82:85] offset:32
	ds_read_b32 v146, v104 offset:16448
	ds_read_b32 v147, v104 offset:17476
	ds_read_b32 v155, v104 offset:18504
	ds_read_b32 v156, v104 offset:19532
	ds_read_b32 v157, v104 offset:20560
	ds_read_b32 v158, v104 offset:21588
	ds_read_b32 v159, v104 offset:22616
	ds_read_b32 v160, v104 offset:23644
	s_waitcnt lgkmcnt(0)
	v_mov_b32_e32 v94, v212
	v_mov_b32_e32 v95, v213
	v_mov_b32_e32 v96, v214
	v_mov_b32_e32 v97, v215
	v_mov_b32_e32 v108, v216
	v_mov_b32_e32 v109, v217
	v_mov_b32_e32 v110, v218
	v_mov_b32_e32 v111, v219
	v_mov_b32_e32 v90, v220
	v_mov_b32_e32 v91, v221
	v_mov_b32_e32 v92, v222
	v_mov_b32_e32 v93, v223
	v_mov_b32_e32 v98, v224
	v_mov_b32_e32 v99, v225
	v_mov_b32_e32 v100, v226
	v_mov_b32_e32 v101, v227
	v_mul_f32_e32 v97, v160, v97
	v_mul_f32_e32 v105, v146, v108
	v_mul_f32_e32 v108, v147, v109
	v_mul_f32_e32 v109, v155, v110
	v_mul_f32_e32 v110, v156, v111
	v_mul_f32_e32 v111, v157, v94
	v_mul_f32_e32 v112, v158, v95
	v_mul_f32_e32 v113, v159, v96
	v_cvt_pk_bf16_f32 v94, v105, v108
	v_cvt_pk_bf16_f32 v95, v109, v110
	v_cvt_pk_bf16_f32 v96, v111, v112
	v_cvt_pk_bf16_f32 v97, v113, v97
	flat_store_dwordx4 v[128:129], v[94:97] offset:64
	ds_read_b32 v161, v104 offset:32896
	ds_read_b32 v162, v104 offset:33924
	ds_read_b32 v163, v104 offset:34952
	ds_read_b32 v164, v104 offset:35980
	ds_read_b32 v165, v104 offset:37008
	ds_read_b32 v166, v104 offset:38036
	ds_read_b32 v167, v104 offset:39064
	ds_read_b32 v168, v104 offset:40092
	s_nop 0
	s_waitcnt lgkmcnt(0)
	v_mov_b32_e32 v178, v228
	v_mov_b32_e32 v179, v229
	v_mov_b32_e32 v180, v230
	v_mov_b32_e32 v181, v231
	v_mov_b32_e32 v182, v232
	v_mov_b32_e32 v183, v233
	v_mov_b32_e32 v184, v234
	v_mov_b32_e32 v185, v235
	v_mov_b32_e32 v102, v236
	v_mov_b32_e32 v103, v237
	v_mov_b32_e32 v104, v238
	v_mov_b32_e32 v105, v239
	v_mov_b32_e32 v110, v240
	v_mov_b32_e32 v111, v241
	v_mov_b32_e32 v112, v242
	v_mov_b32_e32 v113, v243
	v_mul_f32_e32 v169, v165, v178
	v_mul_f32_e32 v106, v161, v182
	v_mul_f32_e32 v107, v162, v183
	v_mul_f32_e32 v108, v163, v184
	v_mul_f32_e32 v109, v164, v185
	v_mul_f32_e32 v172, v166, v179
	v_mul_f32_e32 v173, v167, v180
	v_mul_f32_e32 v174, v168, v181
	v_cvt_pk_bf16_f32 v106, v106, v107
	v_cvt_pk_bf16_f32 v107, v108, v109
	v_cvt_pk_bf16_f32 v108, v169, v172
	v_cvt_pk_bf16_f32 v109, v173, v174
	flat_store_dwordx4 v[128:129], v[106:109] offset:96
	v_add_u32_e32 v128, 0x2020, v154
	ds_write2_b32 v154, v18, v19 offset1:1
	ds_write2_b32 v154, v20, v21 offset0:2 offset1:3
	ds_write2_b32 v128, v22, v23 offset1:1
	v_add_u32_e32 v128, 0x2028, v154
	ds_write2_b32 v128, v24, v25 offset1:1
	v_add_u32_e32 v128, 0x4040, v154
	ds_write2_b32 v128, v34, v35 offset1:1
	v_add_u32_e32 v128, 0x4048, v154
	ds_write2_b32 v128, v36, v37 offset1:1
	v_add_u32_e32 v128, 0x6060, v154
	ds_write2_b32 v128, v38, v39 offset1:1
	v_add_u32_e32 v128, 0x6068, v154
	ds_write2_b32 v128, v40, v41 offset1:1
	v_add_u32_e32 v128, 0x8080, v154
	ds_write2_b32 v128, v50, v51 offset1:1
	v_add_u32_e32 v128, 0x8088, v154
	ds_write2_b32 v128, v52, v53 offset1:1
	v_add_u32_e32 v128, 0xa0a0, v154
	ds_write2_b32 v128, v54, v55 offset1:1
	v_add_u32_e32 v128, 0xa0a8, v154
	ds_write2_b32 v128, v56, v57 offset1:1
	v_add_u32_e32 v128, 0xc0c0, v154
	ds_write2_b32 v128, v58, v59 offset1:1
	v_add_u32_e32 v128, 0xc0c8, v154
	ds_write2_b32 v128, v60, v61 offset1:1
	v_add_u32_e32 v128, 0xe0e0, v154
	ds_write2_b32 v128, v62, v63 offset1:1
	v_add_u32_e32 v128, 0xe0e8, v154
	ds_write2_b32 v128, v64, v65 offset1:1
	s_waitcnt lgkmcnt(0)
	s_barrier
	s_cselect_b64 s[100:101], -1, 0
	s_cbranch_scc1 .LBB0_894
	s_and_b32 s14, s20, 0x1c0
	s_lshl_b32 s2, s2, 6
	v_add_u32_e32 v18, s14, v114
	s_and_b32 s2, s2, 0x7fffff00
	v_ashrrev_i32_e32 v19, 31, v18
	v_lshl_add_u64 v[20:21], s[2:3], 2, v[116:117]
	v_lshlrev_b64 v[18:19], 11, v[18:19]
	v_lshl_add_u64 v[58:59], v[20:21], 0, v[18:19]
	v_add_co_u32_e32 v22, vcc, 0x4000, v58
	s_nop 1
	v_addc_co_u32_e32 v23, vcc, 0, v59, vcc
	v_add_co_u32_e32 v34, vcc, 0x8000, v58
	v_addc_co_u32_e32 v35, vcc, 0, v59, vcc
	v_add_co_u32_e32 v38, vcc, 0xc000, v58
	s_nop 1
	v_addc_co_u32_e32 v39, vcc, 0, v59, vcc
	v_add_co_u32_e32 v50, vcc, 0x10000, v58
	v_addc_co_u32_e32 v51, vcc, 0, v59, vcc
	v_add_co_u32_e32 v54, vcc, 0x14000, v58
	s_nop 1
	v_addc_co_u32_e32 v55, vcc, 0, v59, vcc
	v_add_co_u32_e32 v60, vcc, 0x18000, v58
	v_addc_co_u32_e32 v61, vcc, 0, v59, vcc
	v_add_co_u32_e32 v62, vcc, 0x1c000, v58
	s_nop 1
	v_addc_co_u32_e32 v63, vcc, 0, v59, vcc
.LBB0_894:
	v_mul_f32_e32 v74, v130, v74
	v_mul_f32_e32 v128, v131, v75
	v_mul_f32_e32 v66, v134, v66
	v_mul_f32_e32 v130, v135, v67
	v_mul_f32_e32 v68, v136, v68
	v_mul_f32_e32 v134, v137, v69
	v_lshlrev_b32_e32 v67, 16, v72
	v_and_b32_e32 v131, 0xffff0000, v72
	v_lshlrev_b32_e32 v69, 16, v73
	v_and_b32_e32 v135, 0xffff0000, v73
	v_mul_f32_e32 v76, v132, v76
	v_mul_f32_e32 v132, v133, v77
	v_lshlrev_b32_e32 v75, 16, v70
	v_and_b32_e32 v129, 0xffff0000, v70
	v_lshlrev_b32_e32 v77, 16, v71
	v_and_b32_e32 v133, 0xffff0000, v71
	v_mul_f32_e32 v70, v138, v86
	v_mul_f32_e32 v136, v139, v87
	v_mul_f32_e32 v86, v140, v88
	v_mul_f32_e32 v138, v141, v89
	v_lshlrev_b32_e32 v71, 16, v82
	v_and_b32_e32 v137, 0xffff0000, v82
	v_lshlrev_b32_e32 v87, 16, v83
	v_and_b32_e32 v139, 0xffff0000, v83
	v_pk_add_f32 v[66:67], v[66:67], v[130:131]
	v_pk_add_f32 v[68:69], v[68:69], v[134:135]
	v_mul_f32_e32 v72, v142, v78
	v_mul_f32_e32 v88, v143, v79
	v_mul_f32_e32 v78, v144, v80
	v_mul_f32_e32 v80, v145, v81
	v_lshlrev_b32_e32 v73, 16, v84
	v_and_b32_e32 v89, 0xffff0000, v84
	v_lshlrev_b32_e32 v79, 16, v85
	v_and_b32_e32 v81, 0xffff0000, v85
	v_pk_add_f32 v[66:67], v[66:67], v[68:69]
	v_pk_add_f32 v[68:69], v[70:71], v[136:137]
	v_pk_add_f32 v[70:71], v[86:87], v[138:139]
	v_mul_f32_e32 v82, v146, v98
	v_pk_add_f32 v[68:69], v[68:69], v[70:71]
	v_pk_add_f32 v[70:71], v[72:73], v[88:89]
	v_pk_add_f32 v[72:73], v[78:79], v[80:81]
	v_mul_f32_e32 v140, v147, v99
	v_mul_f32_e32 v98, v155, v100
	v_mul_f32_e32 v142, v156, v101
	v_lshlrev_b32_e32 v83, 16, v94
	v_and_b32_e32 v141, 0xffff0000, v94
	v_lshlrev_b32_e32 v99, 16, v95
	v_and_b32_e32 v143, 0xffff0000, v95
	v_pk_add_f32 v[74:75], v[74:75], v[128:129]
	v_pk_add_f32 v[76:77], v[76:77], v[132:133]
	v_pk_add_f32 v[70:71], v[70:71], v[72:73]
	v_mul_f32_e32 v84, v157, v90
	v_mul_f32_e32 v100, v158, v91
	v_mul_f32_e32 v90, v159, v92
	v_mul_f32_e32 v92, v160, v93
	v_lshlrev_b32_e32 v85, 16, v96
	v_and_b32_e32 v101, 0xffff0000, v96
	v_lshlrev_b32_e32 v91, 16, v97
	v_and_b32_e32 v93, 0xffff0000, v97
	v_pk_add_f32 v[74:75], v[74:75], v[76:77]
	v_pk_add_f32 v[68:69], v[68:69], v[70:71]
	v_pk_add_f32 v[70:71], v[82:83], v[140:141]
	v_pk_add_f32 v[72:73], v[98:99], v[142:143]
	v_pk_add_f32 v[66:67], v[74:75], v[66:67]
	v_pk_add_f32 v[70:71], v[70:71], v[72:73]
	v_pk_add_f32 v[72:73], v[84:85], v[100:101]
	v_pk_add_f32 v[74:75], v[90:91], v[92:93]
	v_mul_f32_e32 v94, v161, v110
	v_mul_f32_e32 v144, v162, v111
	v_mul_f32_e32 v110, v163, v112
	v_mul_f32_e32 v146, v164, v113
	v_lshlrev_b32_e32 v95, 16, v106
	v_and_b32_e32 v145, 0xffff0000, v106
	v_lshlrev_b32_e32 v111, 16, v107
	v_and_b32_e32 v147, 0xffff0000, v107
	v_pk_add_f32 v[72:73], v[72:73], v[74:75]
	s_add_i32 s2, s19, -3
	v_mul_f32_e32 v96, v165, v102
	v_mul_f32_e32 v112, v166, v103
	v_mul_f32_e32 v102, v167, v104
	v_mul_f32_e32 v104, v168, v105
	v_lshlrev_b32_e32 v97, 16, v108
	v_and_b32_e32 v113, 0xffff0000, v108
	v_lshlrev_b32_e32 v103, 16, v109
	v_and_b32_e32 v105, 0xffff0000, v109
	v_pk_add_f32 v[70:71], v[70:71], v[72:73]
	v_pk_add_f32 v[72:73], v[94:95], v[144:145]
	v_pk_add_f32 v[74:75], v[110:111], v[146:147]
	s_and_b32 s14, s2, 6
	v_pk_add_f32 v[72:73], v[72:73], v[74:75]
	v_pk_add_f32 v[74:75], v[96:97], v[112:113]
	v_pk_add_f32 v[76:77], v[102:103], v[104:105]
	v_pk_add_f32 v[66:67], v[124:125], v[66:67]
	s_lshl_b32 s2, s14, 6
	v_pk_add_f32 v[74:75], v[74:75], v[76:77]
	v_pk_add_f32 v[66:67], v[66:67], v[68:69]
	v_readlane_b32 s24, v251, 37
	v_pk_add_f32 v[72:73], v[72:73], v[74:75]
	v_pk_add_f32 v[66:67], v[66:67], v[70:71]
	s_or_b32 s15, s2, s22
	v_readlane_b32 s25, v251, 38
	v_pk_add_f32 v[74:75], v[66:67], v[72:73]
	v_add_u32_e32 v66, v149, v151
	v_lshl_add_u64 v[72:73], s[24:25], 0, v[126:127]
	s_lshl_b32 s24, s15, 2
	s_mov_b32 s25, s3
	v_lshl_add_u64 v[110:111], v[118:119], 0, s[24:25]
	v_lshl_add_u64 v[92:93], v[120:121], 0, s[24:25]
	ds_read_b32 v85, v66
	ds_read_b32 v87, v66 offset:1028
	ds_read_b32 v89, v66 offset:2056
	ds_read_b32 v91, v66 offset:3084
	ds_read_b32 v98, v66 offset:4112
	ds_read_b32 v99, v66 offset:5140
	ds_read_b32 v100, v66 offset:6168
	ds_read_b32 v101, v66 offset:7196
	global_load_dwordx4 v[66:69], v[110:111], off offset:272
	global_load_dwordx4 v[94:97], v[110:111], off offset:256
	global_load_dwordx4 v[76:79], v[92:93], off offset:272
	global_load_dwordx4 v[80:83], v[92:93], off offset:256
	global_load_dwordx4 v[186:189], v[110:111], off offset:336
	global_load_dwordx4 v[190:193], v[110:111], off offset:320
	global_load_dwordx4 v[194:197], v[92:93], off offset:336
	global_load_dwordx4 v[198:201], v[92:93], off offset:320
	global_load_dwordx4 v[212:215], v[110:111], off offset:400
	global_load_dwordx4 v[216:219], v[110:111], off offset:384
	global_load_dwordx4 v[220:223], v[92:93], off offset:400
	global_load_dwordx4 v[224:227], v[92:93], off offset:384
	global_load_dwordx4 v[228:231], v[110:111], off offset:464
	global_load_dwordx4 v[232:235], v[110:111], off offset:448
	global_load_dwordx4 v[236:239], v[92:93], off offset:464
	global_load_dwordx4 v[240:243], v[92:93], off offset:448
	s_mov_b64 vcc, s[100:101]
	s_cbranch_vccnz .Lfold_skip_f1B
	global_load_dwordx4 v[18:21], v[58:59], off nt
	global_load_dwordx4 v[22:25], v[22:23], off nt
	global_load_dwordx4 v[34:37], v[34:35], off nt
	global_load_dwordx4 v[38:41], v[38:39], off nt
	global_load_dwordx4 v[50:53], v[50:51], off nt
	global_load_dwordx4 v[54:57], v[54:55], off nt
	global_load_dwordx4 v[58:61], v[60:61], off nt
	global_load_dwordx4 v[62:65], v[62:63], off nt
	s_waitcnt vmcnt(8)
	s_branch .Lfold_join_f1B

.Lfold_join_f1B:
	s_lshl_b32 s2, s15, 1
	s_bitset1_b32 s2, 7
	v_lshl_add_u64 v[70:71], v[72:73], 0, s[2:3]
	v_lshl_add_u64 v[72:73], v[72:73], 0, v[0:1]
	v_lshl_add_u64 v[72:73], v[72:73], 0, s[2:3]
	v_add_u32_e32 v140, v149, v152
	v_lshl_add_u64 v[136:137], v[70:71], 0, v[0:1]
	s_cmp_lg_u32 s14, 6
	s_waitcnt lgkmcnt(0)
	v_mul_f32_e32 v69, v101, v69
	v_mul_f32_e32 v88, v85, v80
	v_mul_f32_e32 v90, v87, v81
	v_mul_f32_e32 v84, v89, v82
	v_mul_f32_e32 v86, v91, v83
	v_mul_f32_e32 v80, v98, v76
	v_mul_f32_e32 v82, v99, v77
	v_mul_f32_e32 v76, v100, v78
	v_mul_f32_e32 v78, v101, v79
	v_mul_f32_e32 v77, v85, v94
	v_mul_f32_e32 v79, v87, v95
	v_mul_f32_e32 v81, v89, v96
	v_mul_f32_e32 v83, v91, v97
	v_mul_f32_e32 v85, v98, v66
	v_mul_f32_e32 v87, v99, v67
	v_mul_f32_e32 v89, v100, v68
	v_cvt_pk_bf16_f32 v66, v77, v79
	v_cvt_pk_bf16_f32 v67, v81, v83
	v_cvt_pk_bf16_f32 v68, v85, v87
	v_cvt_pk_bf16_f32 v69, v89, v69
	flat_store_dwordx4 v[72:73], v[66:69]
	v_lshlrev_b32_e32 v89, 16, v66
	v_and_b32_e32 v91, 0xffff0000, v66
	v_lshlrev_b32_e32 v85, 16, v67
	v_and_b32_e32 v87, 0xffff0000, v67
	v_lshlrev_b32_e32 v81, 16, v68
	v_and_b32_e32 v83, 0xffff0000, v68
	v_lshlrev_b32_e32 v77, 16, v69
	v_and_b32_e32 v79, 0xffff0000, v69
	ds_read_b32 v72, v140
	ds_read_b32 v73, v140 offset:1028
	ds_read_b32 v103, v140 offset:2056
	ds_read_b32 v105, v140 offset:3084
	ds_read_b32 v107, v140 offset:4112
	ds_read_b32 v109, v140 offset:5140
	ds_read_b32 v112, v140 offset:6168
	ds_read_b32 v113, v140 offset:7196
	v_pk_add_f32 v[88:89], v[88:89], v[90:91]
	v_pk_add_f32 v[84:85], v[84:85], v[86:87]
	v_pk_add_f32 v[80:81], v[80:81], v[82:83]
	v_pk_add_f32 v[76:77], v[76:77], v[78:79]
	v_pk_add_f32 v[84:85], v[88:89], v[84:85]
	v_pk_add_f32 v[76:77], v[80:81], v[76:77]
	s_waitcnt lgkmcnt(0)
	v_mov_b32_e32 v66, v186
	v_mov_b32_e32 v67, v187
	v_mov_b32_e32 v68, v188
	v_mov_b32_e32 v69, v189
	v_mov_b32_e32 v124, v190
	v_mov_b32_e32 v125, v191
	v_mov_b32_e32 v126, v192
	v_mov_b32_e32 v127, v193
	v_mov_b32_e32 v94, v194
	v_mov_b32_e32 v95, v195
	v_mov_b32_e32 v96, v196
	v_mov_b32_e32 v97, v197
	v_mov_b32_e32 v98, v198
	v_mov_b32_e32 v99, v199
	v_mov_b32_e32 v100, v200
	v_mov_b32_e32 v101, v201
	v_mul_f32_e32 v69, v113, v69
	v_pk_add_f32 v[76:77], v[84:85], v[76:77]
	v_mul_f32_e32 v106, v72, v98
	v_mul_f32_e32 v108, v73, v99
	v_mul_f32_e32 v102, v103, v100
	v_mul_f32_e32 v104, v105, v101
	v_mul_f32_e32 v98, v107, v94
	v_mul_f32_e32 v100, v109, v95
	v_mul_f32_e32 v94, v112, v96
	v_mul_f32_e32 v96, v113, v97
	v_mul_f32_e32 v72, v72, v124
	v_mul_f32_e32 v73, v73, v125
	v_mul_f32_e32 v95, v103, v126
	v_mul_f32_e32 v97, v105, v127
	v_mul_f32_e32 v99, v107, v66
	v_mul_f32_e32 v101, v109, v67
	v_mul_f32_e32 v103, v112, v68
	v_cvt_pk_bf16_f32 v66, v72, v73
	v_cvt_pk_bf16_f32 v67, v95, v97
	v_cvt_pk_bf16_f32 v68, v99, v101
	v_cvt_pk_bf16_f32 v69, v103, v69
	flat_store_dwordx4 v[136:137], v[66:69] offset:32
	v_lshlrev_b32_e32 v107, 16, v66
	v_and_b32_e32 v109, 0xffff0000, v66
	v_lshlrev_b32_e32 v103, 16, v67
	v_and_b32_e32 v105, 0xffff0000, v67
	v_lshlrev_b32_e32 v99, 16, v68
	v_and_b32_e32 v101, 0xffff0000, v68
	v_lshlrev_b32_e32 v95, 16, v69
	v_and_b32_e32 v97, 0xffff0000, v69
	ds_read_b32 v113, v140 offset:16448
	ds_read_b32 v129, v140 offset:17476
	ds_read_b32 v131, v140 offset:18504
	ds_read_b32 v133, v140 offset:19532
	ds_read_b32 v135, v140 offset:20560
	ds_read_b32 v139, v140 offset:21588
	ds_read_b32 v141, v140 offset:22616
	ds_read_b32 v146, v140 offset:23644
	v_pk_add_f32 v[74:75], v[74:75], v[76:77]
	v_pk_add_f32 v[76:77], v[106:107], v[108:109]
	v_pk_add_f32 v[78:79], v[102:103], v[104:105]
	v_pk_add_f32 v[80:81], v[94:95], v[96:97]
	v_pk_add_f32 v[76:77], v[76:77], v[78:79]
	v_pk_add_f32 v[78:79], v[98:99], v[100:101]
	s_waitcnt lgkmcnt(0)
	v_mov_b32_e32 v66, v212
	v_mov_b32_e32 v67, v213
	v_mov_b32_e32 v68, v214
	v_mov_b32_e32 v69, v215
	v_mov_b32_e32 v70, v216
	v_mov_b32_e32 v71, v217
	v_mov_b32_e32 v72, v218
	v_mov_b32_e32 v73, v219
	v_mov_b32_e32 v142, v220
	v_mov_b32_e32 v143, v221
	v_mov_b32_e32 v144, v222
	v_mov_b32_e32 v145, v223
	v_mov_b32_e32 v124, v224
	v_mov_b32_e32 v125, v225
	v_mov_b32_e32 v126, v226
	v_mov_b32_e32 v127, v227
	v_mul_f32_e32 v69, v146, v69
	v_mul_f32_e32 v70, v113, v70
	v_mul_f32_e32 v71, v129, v71
	v_mul_f32_e32 v134, v113, v124
	v_mul_f32_e32 v138, v129, v125
	v_mul_f32_e32 v132, v133, v127
	v_mul_f32_e32 v72, v131, v72
	v_mul_f32_e32 v73, v133, v73
	v_mul_f32_e32 v113, v135, v66
	v_mul_f32_e32 v125, v139, v67
	v_mul_f32_e32 v127, v141, v68
	v_cvt_pk_bf16_f32 v66, v70, v71
	v_cvt_pk_bf16_f32 v67, v72, v73
	v_cvt_pk_bf16_f32 v68, v113, v125
	v_cvt_pk_bf16_f32 v69, v127, v69
	flat_store_dwordx4 v[136:137], v[66:69] offset:64
	v_mul_f32_e32 v130, v131, v126
	v_mul_f32_e32 v126, v135, v142
	v_mul_f32_e32 v128, v139, v143
	v_mul_f32_e32 v112, v141, v144
	v_mul_f32_e32 v124, v146, v145
	v_lshlrev_b32_e32 v135, 16, v66
	v_and_b32_e32 v139, 0xffff0000, v66
	v_lshlrev_b32_e32 v131, 16, v67
	v_and_b32_e32 v133, 0xffff0000, v67
	v_lshlrev_b32_e32 v127, 16, v68
	v_and_b32_e32 v129, 0xffff0000, v68
	v_lshlrev_b32_e32 v113, 16, v69
	v_and_b32_e32 v125, 0xffff0000, v69
	ds_read_b32 v141, v140 offset:32896
	ds_read_b32 v143, v140 offset:33924
	ds_read_b32 v155, v140 offset:34952
	ds_read_b32 v160, v140 offset:35980
	ds_read_b32 v161, v140 offset:37008
	ds_read_b32 v162, v140 offset:38036
	ds_read_b32 v163, v140 offset:39064
	ds_read_b32 v164, v140 offset:40092
	v_pk_add_f32 v[78:79], v[78:79], v[80:81]
	v_pk_add_f32 v[80:81], v[112:113], v[124:125]
	v_pk_add_f32 v[76:77], v[76:77], v[78:79]
	v_pk_add_f32 v[78:79], v[130:131], v[132:133]
	v_pk_add_f32 v[74:75], v[74:75], v[76:77]
	v_pk_add_f32 v[76:77], v[134:135], v[138:139]
	s_waitcnt lgkmcnt(0)
	v_mov_b32_e32 v144, v228
	v_mov_b32_e32 v145, v229
	v_mov_b32_e32 v146, v230
	v_mov_b32_e32 v147, v231
	v_mov_b32_e32 v156, v232
	v_mov_b32_e32 v157, v233
	v_mov_b32_e32 v158, v234
	v_mov_b32_e32 v159, v235
	v_mov_b32_e32 v66, v236
	v_mov_b32_e32 v67, v237
	v_mov_b32_e32 v68, v238
	v_mov_b32_e32 v69, v239
	v_mov_b32_e32 v70, v240
	v_mov_b32_e32 v71, v241
	v_mov_b32_e32 v72, v242
	v_mov_b32_e32 v73, v243
	v_mul_f32_e32 v93, v161, v144
	v_pk_add_f32 v[76:77], v[76:77], v[78:79]
	v_pk_add_f32 v[78:79], v[126:127], v[128:129]
	v_mul_f32_e32 v140, v141, v70
	v_mul_f32_e32 v142, v143, v71
	v_mul_f32_e32 v92, v155, v72
	v_mul_f32_e32 v110, v160, v73
	v_mul_f32_e32 v70, v161, v66
	v_mul_f32_e32 v72, v162, v67
	v_mul_f32_e32 v66, v163, v68
	v_mul_f32_e32 v68, v164, v69
	v_mul_f32_e32 v67, v141, v156
	v_mul_f32_e32 v69, v143, v157
	v_mul_f32_e32 v71, v155, v158
	v_mul_f32_e32 v73, v160, v159
	v_mul_f32_e32 v111, v162, v145
	v_mul_f32_e32 v141, v163, v146
	v_mul_f32_e32 v143, v164, v147
	v_pk_add_f32 v[78:79], v[78:79], v[80:81]
	v_cvt_pk_bf16_f32 v144, v67, v69
	v_cvt_pk_bf16_f32 v145, v71, v73
	v_cvt_pk_bf16_f32 v146, v93, v111
	v_cvt_pk_bf16_f32 v147, v141, v143
	flat_store_dwordx4 v[136:137], v[144:147] offset:96
	v_lshlrev_b32_e32 v141, 16, v144
	v_and_b32_e32 v143, 0xffff0000, v144
	v_lshlrev_b32_e32 v93, 16, v145
	v_and_b32_e32 v111, 0xffff0000, v145
	v_lshlrev_b32_e32 v71, 16, v146
	v_and_b32_e32 v73, 0xffff0000, v146
	v_lshlrev_b32_e32 v67, 16, v147
	v_and_b32_e32 v69, 0xffff0000, v147
	v_pk_add_f32 v[76:77], v[76:77], v[78:79]
	v_pk_add_f32 v[78:79], v[92:93], v[110:111]
	v_pk_add_f32 v[74:75], v[74:75], v[76:77]
	v_pk_add_f32 v[76:77], v[140:141], v[142:143]
	v_pk_add_f32 v[70:71], v[70:71], v[72:73]
	v_pk_add_f32 v[66:67], v[66:67], v[68:69]
	v_pk_add_f32 v[76:77], v[76:77], v[78:79]
	v_pk_add_f32 v[66:67], v[70:71], v[66:67]
	s_nop 0
	v_pk_add_f32 v[66:67], v[76:77], v[66:67]
	s_nop 0
	v_pk_add_f32 v[124:125], v[74:75], v[66:67]
	s_cbranch_scc1 .LBB0_889
	ds_bpermute_b32 v66, v150, v125
	ds_bpermute_b32 v67, v150, v124
	s_and_saveexec_b64 s[14:15], s[0:1]
	s_cbranch_execz .LBB0_888
	s_lshl_b32 s2, s22, 2
	s_add_u32 s22, s17, s2
	s_addc_u32 s23, s18, 0
	s_waitcnt lgkmcnt(0)
	v_add_f32_e32 v68, v124, v67
	v_add_f32_e32 v69, v125, v66
	v_lshl_add_u64 v[66:67], v[122:123], 2, s[22:23]
	flat_store_dword v[66:67], v69
	v_add_co_u32_e32 v66, vcc, 0x2000, v66
	s_nop 1
	v_addc_co_u32_e32 v67, vcc, 0, v67, vcc
	flat_store_dword v[66:67], v68
	s_branch .LBB0_888

; #define CW_LOAD(v, j) do { bool _ok; int _k0, _n0; CW_COORD(j, _ok, _k0, _n0); if (_ok) { _Pragma("unroll") for (int i = 0; i < 8; ++i) v[i] = __builtin_nontemporal_load((const f32x4*)(W + (size_t)(_k0 + lk + 8 * i) * N + _n0 + ln4)); } } while (0)
; template <bool FOLD> ...
;     ...
;     if (vbid < 0) return;
;     const int G = vG, bid = vbid, ntk = K >> 6, nt_all = ntk * (N >> 8), nunits = (N >> 8) * 4, u0 = vbid;
;     const int lk = tid >> 6, ln4 = (tid & 63) << 2, n = tid >> 1, par = tid & 1;
;     float csum = 0.f, bsum = 0.f;
;     ...
;     f32x4 va[8], vb[8];
;     CW_LOAD(va, 0); CW_LOAD(vb, 1);
.LBB0_901:
	s_cmp_lt_i32 s18, 0
	s_cbranch_scc1 .LBB0_913
	s_mov_b64 s[6:7], s[36:37]
	s_load_dwordx4 s[20:23], s[10:11], 0xa8
	s_mul_i32 s0, s6, 0x3c00000
	s_mul_hi_i32 s1, s6, 0x3c00000
	s_waitcnt lgkmcnt(0)
	s_add_u32 s0, s14, s0
	s_addc_u32 s1, s15, s1
	s_lshl_b64 s[6:7], s[36:37], 13
	s_add_u32 s2, s6, 0xffffe000
	s_addc_u32 s17, s7, -1
	s_add_u32 s6, s20, s2
	s_addc_u32 s7, s21, s17
	s_add_u32 s16, s22, s2
	s_addc_u32 s17, s23, s17
	s_lshl_b32 s2, s18, 9
	s_and_b32 s19, s2, 0x600
	s_lshl_b32 s2, s18, 6
	s_and_b32 s2, s2, 0x7fffff00
	v_lshlrev_b32_e32 v68, 2, v210
	s_lshl_b64 s[20:21], s[2:3], 2
	v_ashrrev_i32_e32 v67, 6, v210
	v_and_b32_e32 v0, 0xfc, v68
	s_add_u32 s20, s0, s20
	v_add_u32_e32 v146, s19, v67
	s_addc_u32 s21, s1, s21
	v_lshlrev_b32_e32 v0, 2, v0
	s_waitcnt vmcnt(0)
	v_lshl_add_u64 v[58:59], s[20:21], 0, v[0:1]
	v_add_u32_e32 v4, 8, v146
	v_add_u32_e32 v10, 16, v146
	v_add_u32_e32 v12, 24, v146
	v_add_u32_e32 v18, 32, v146
	v_add_u32_e32 v20, 40, v146
	v_mad_i64_i32 v[2:3], s[20:21], v146, s30, v[58:59]
	v_mad_i64_i32 v[6:7], s[20:21], v4, s30, v[58:59]
	v_mad_i64_i32 v[10:11], s[20:21], v10, s30, v[58:59]
	v_mad_i64_i32 v[14:15], s[20:21], v12, s30, v[58:59]
	v_mad_i64_i32 v[18:19], s[20:21], v18, s30, v[58:59]
	v_mad_i64_i32 v[20:21], s[20:21], v20, s30, v[58:59]
	global_load_dwordx4 v[2:5], v[2:3], off nt
	s_nop 0
	global_load_dwordx4 v[6:9], v[6:7], off nt
	s_nop 0
	global_load_dwordx4 v[10:13], v[10:11], off nt
	s_nop 0
	global_load_dwordx4 v[14:17], v[14:15], off nt
	s_nop 0
	global_load_dwordx4 v[22:25], v[18:19], off nt
	global_load_dwordx4 v[30:33], v[20:21], off nt
	v_add_u32_e32 v18, 48, v146
	v_add_u32_e32 v20, 56, v146
	v_mad_i64_i32 v[18:19], s[20:21], v18, s30, v[58:59]
	v_mad_i64_i32 v[20:21], s[20:21], v20, s30, v[58:59]
	global_load_dwordx4 v[38:41], v[18:19], off nt
	global_load_dwordx4 v[46:49], v[20:21], off nt
	v_add_u32_e32 v18, 64, v146
	v_add_u32_e32 v20, 0x48, v146
	v_add_u32_e32 v34, 0x50, v146
	v_add_u32_e32 v36, 0x58, v146
	v_add_u32_e32 v50, 0x60, v146
	v_add_u32_e32 v52, 0x68, v146
	v_add_u32_e32 v60, 0x70, v146
	v_add_u32_e32 v62, 0x78, v146
	v_mad_i64_i32 v[18:19], s[20:21], v18, s30, v[58:59]
	v_mad_i64_i32 v[26:27], s[20:21], v20, s30, v[58:59]
	v_mad_i64_i32 v[34:35], s[20:21], v34, s30, v[58:59]
	v_mad_i64_i32 v[42:43], s[20:21], v36, s30, v[58:59]
	v_mad_i64_i32 v[50:51], s[20:21], v50, s30, v[58:59]
	v_mad_i64_i32 v[54:55], s[20:21], v52, s30, v[58:59]
	v_mad_i64_i32 v[60:61], s[20:21], v60, s30, v[58:59]
	v_mad_i64_i32 v[62:63], s[20:21], v62, s30, v[58:59]
	global_load_dwordx4 v[18:21], v[18:19], off nt
	s_nop 0
	global_load_dwordx4 v[26:29], v[26:27], off nt
	s_nop 0
	global_load_dwordx4 v[34:37], v[34:35], off nt
	s_nop 0
	global_load_dwordx4 v[42:45], v[42:43], off nt
	s_nop 0
	global_load_dwordx4 v[50:53], v[50:51], off nt
	s_nop 0
	global_load_dwordx4 v[54:57], v[54:55], off nt
	s_nop 0
	global_load_dwordx4 v[58:61], v[60:61], off nt
	s_nop 0
	global_load_dwordx4 v[62:65], v[62:63], off nt
	v_ashrrev_i32_e32 v147, 1, v210
	v_and_b32_e32 v66, 63, v147
	v_lshlrev_b32_e32 v71, 1, v66
	v_subrev_u32_e32 v72, 63, v71
	v_cmp_gt_u32_e32 vcc, 32, v66
	v_and_b32_e32 v69, 1, v210
	v_lshl_add_u64 v[114:115], s[0:1], 0, v[0:1]
	v_cndmask_b32_e32 v71, v72, v71, vcc
	v_sub_u32_e32 v148, v71, v66
	v_lshlrev_b32_e32 v66, 3, v69
	v_readlane_b32 s0, v250, 62
	v_add_u32_e32 v70, 0, v0
	s_movk_i32 s2, 0x404
	v_add_u32_e32 v72, s0, v0
	v_or_b32_e32 v0, 16, v66
	v_lshlrev_b32_e32 v71, 2, v147
	v_mul_lo_u32 v67, v67, s2
	v_mul_u32_u24_e32 v153, 0x404, v0
	v_lshlrev_b32_e32 v0, 5, v69
	v_mov_b32_e32 v122, 0
	s_mov_b32 s19, 3
	v_add_u32_e32 v149, 0, v71
	v_add_u32_e32 v150, s0, v71
	v_bitop3_b32 v151, v68, 4, v205 bitop3:0x6c
	v_cmp_eq_u32_e64 s[0:1], 0, v69
	v_mul_u32_u24_e32 v152, 0x2020, v69
	v_lshl_add_u64 v[116:117], s[6:7], 0, v[0:1]
	v_lshl_add_u64 v[118:119], s[16:17], 0, v[0:1]
	s_movk_i32 s20, 0xc0
	v_add_u32_e32 v154, v70, v67
	v_add_u32_e32 v155, v72, v67
	v_lshlrev_b32_e32 v0, 1, v66
	s_mov_b32 s16, s18
	v_mov_b32_e32 v123, v122
	s_waitcnt vmcnt(0)
	s_branch .LBB0_905

.LBB0_905:
	s_waitcnt lgkmcnt(0)
	v_add_u32_e32 v66, 0x2020, v154
	ds_write2_b32 v154, v2, v3 offset1:1
	ds_write2_b32 v154, v4, v5 offset0:2 offset1:3
	ds_write2_b32 v66, v6, v7 offset1:1
	v_add_u32_e32 v66, 0x2028, v154
	ds_write2_b32 v66, v8, v9 offset1:1
	v_add_u32_e32 v66, 0x4040, v154
	ds_write2_b32 v66, v10, v11 offset1:1
	v_add_u32_e32 v66, 0x4048, v154
	ds_write2_b32 v66, v12, v13 offset1:1
	v_add_u32_e32 v66, 0x6060, v154
	ds_write2_b32 v66, v14, v15 offset1:1
	v_add_u32_e32 v66, 0x6068, v154
	ds_write2_b32 v66, v16, v17 offset1:1
	v_add_u32_e32 v66, 0x8080, v154
	ds_write2_b32 v66, v22, v23 offset1:1
	v_add_u32_e32 v66, 0x8088, v154
	s_add_i32 s2, s19, -1
	ds_write2_b32 v66, v24, v25 offset1:1
	v_add_u32_e32 v66, 0xa0a0, v154
	s_lshr_b32 s2, s2, 3
	ds_write2_b32 v66, v30, v31 offset1:1
	v_add_u32_e32 v66, 0xa0a8, v154
	s_mul_i32 s21, s2, 0x78
	ds_write2_b32 v66, v32, v33 offset1:1
	v_add_u32_e32 v66, 0xc0c0, v154
	s_add_i32 s21, s21, s18
	ds_write2_b32 v66, v38, v39 offset1:1
	v_add_u32_e32 v66, 0xc0c8, v154
	s_cmpk_gt_i32 s21, 0x77
	ds_write2_b32 v66, v40, v41 offset1:1
	v_add_u32_e32 v66, 0xe0e0, v154
	s_cselect_b64 s[6:7], -1, 0
	ds_write2_b32 v66, v46, v47 offset1:1
	v_add_u32_e32 v66, 0xe0e8, v154
	s_and_b64 vcc, exec, s[6:7]
	ds_write2_b32 v66, v48, v49 offset1:1
	s_waitcnt lgkmcnt(0)
	s_barrier
	s_mov_b64 s[100:101], vcc
	s_cbranch_vccnz .LBB0_907
	s_sub_i32 s2, s20, 64
	s_and_b32 s17, s2, 0x180
	s_lshl_b32 s2, s21, 6
	s_and_b32 s2, s2, 0x7fffff00
	v_add_u32_e32 v46, s17, v146
	v_lshl_add_u64 v[38:39], s[2:3], 2, v[114:115]
	v_mad_i64_i32 v[2:3], s[22:23], v46, s30, v[38:39]
	v_add_u32_e32 v4, 8, v46
	v_add_u32_e32 v10, 16, v46
	v_add_u32_e32 v12, 24, v46
	v_add_u32_e32 v22, 32, v46
	v_add_u32_e32 v24, 40, v46
	v_add_u32_e32 v40, 48, v46
	v_add_u32_e32 v46, 56, v46
	v_mad_i64_i32 v[6:7], s[22:23], v4, s30, v[38:39]
	v_mad_i64_i32 v[10:11], s[22:23], v10, s30, v[38:39]
	v_mad_i64_i32 v[14:15], s[22:23], v12, s30, v[38:39]
	v_mad_i64_i32 v[22:23], s[22:23], v22, s30, v[38:39]
	v_mad_i64_i32 v[30:31], s[22:23], v24, s30, v[38:39]
	v_mad_i64_i32 v[40:41], s[22:23], v40, s30, v[38:39]
	v_mad_i64_i32 v[46:47], s[22:23], v46, s30, v[38:39]
.LBB0_907:
	s_add_i32 s2, s20, 0xffffff40
	s_lshl_b32 s17, s16, 9
	s_lshl_b32 s16, s16, 6
	s_and_b32 s16, s16, 0x7fffff00
	s_and_b32 s2, s2, 0x180
	s_and_b32 s22, s17, 0x600
	s_or_b32 s2, s2, s22
	v_add_u32_e32 v66, s16, v147
	v_add_u32_e32 v67, 0xfffff800, v66
	s_lshl_b32 s16, s2, 1
	v_cmp_gt_u32_e32 vcc, s31, v67
	s_add_u32 s16, s42, s16
	s_addc_u32 s17, s43, 0
	v_cndmask_b32_e32 v67, 0, v148, vcc
	s_lshl_b32 s2, s2, 2
	v_add_u32_e32 v120, v67, v66
	v_add_u32_e32 v66, v149, v152
	v_lshl_add_u64 v[102:103], v[116:117], 0, s[2:3]
	ds_read_b32 v128, v66
	ds_read_b32 v129, v66 offset:1028
	ds_read_b32 v130, v66 offset:2056
	ds_read_b32 v131, v66 offset:3084
	ds_read_b32 v132, v66 offset:4112
	ds_read_b32 v133, v66 offset:5140
	ds_read_b32 v134, v66 offset:6168
	ds_read_b32 v135, v66 offset:7196
	global_load_dwordx4 v[70:73], v[102:103], off offset:16
	global_load_dwordx4 v[78:81], v[102:103], off
	v_ashrrev_i32_e32 v121, 31, v120
	v_lshlrev_b64 v[124:125], 12, v[120:121]
	v_lshl_add_u64 v[82:83], s[16:17], 0, v[124:125]
	v_lshl_add_u64 v[106:107], v[118:119], 0, s[2:3]
	v_lshl_add_u64 v[126:127], v[82:83], 0, v[0:1]
	global_load_dwordx4 v[66:69], v[106:107], off offset:16
	global_load_dwordx4 v[74:77], v[106:107], off
	global_load_dwordx4 v[186:189], v[102:103], off offset:80
	global_load_dwordx4 v[190:193], v[102:103], off offset:64
	global_load_dwordx4 v[194:197], v[106:107], off offset:80
	global_load_dwordx4 v[198:201], v[106:107], off offset:64
	global_load_dwordx4 v[212:215], v[102:103], off offset:144
	global_load_dwordx4 v[216:219], v[102:103], off offset:128
	global_load_dwordx4 v[220:223], v[106:107], off offset:144
	global_load_dwordx4 v[224:227], v[106:107], off offset:128
	global_load_dwordx4 v[228:231], v[102:103], off offset:208
	global_load_dwordx4 v[232:235], v[102:103], off offset:192
	global_load_dwordx4 v[236:239], v[106:107], off offset:208
	global_load_dwordx4 v[240:243], v[106:107], off offset:192
	s_mov_b64 vcc, s[100:101]
	s_cbranch_vccnz .Lfold_skip_f2A
	global_load_dwordx4 v[2:5], v[2:3], off nt
	global_load_dwordx4 v[6:9], v[6:7], off nt
	global_load_dwordx4 v[10:13], v[10:11], off nt
	global_load_dwordx4 v[14:17], v[14:15], off nt
	global_load_dwordx4 v[22:25], v[22:23], off nt
	global_load_dwordx4 v[30:33], v[30:31], off nt
	global_load_dwordx4 v[38:41], v[40:41], off nt
	global_load_dwordx4 v[46:49], v[46:47], off nt
	s_waitcnt vmcnt(8)
	s_branch .Lfold_join_f2A

.Lfold_join_f2A:
	v_add_u32_e32 v104, v149, v153
	s_lshr_b32 s2, s19, 3
	s_mulk_i32 s2, 0x78
	s_add_i32 s2, s2, s18
	s_cmpk_gt_i32 s2, 0x77
	s_waitcnt lgkmcnt(0)
	v_mul_f32_e32 v73, v135, v73
	v_mul_f32_e32 v78, v128, v78
	v_mul_f32_e32 v79, v129, v79
	v_mul_f32_e32 v80, v130, v80
	v_mul_f32_e32 v81, v131, v81
	v_mul_f32_e32 v84, v132, v70
	v_mul_f32_e32 v85, v133, v71
	v_mul_f32_e32 v86, v134, v72
	v_cvt_pk_bf16_f32 v70, v78, v79
	v_cvt_pk_bf16_f32 v71, v80, v81
	v_cvt_pk_bf16_f32 v72, v84, v85
	v_cvt_pk_bf16_f32 v73, v86, v73
	flat_store_dwordx4 v[126:127], v[70:73]
	ds_read_b32 v136, v104
	ds_read_b32 v137, v104 offset:1028
	ds_read_b32 v138, v104 offset:2056
	ds_read_b32 v139, v104 offset:3084
	ds_read_b32 v140, v104 offset:4112
	ds_read_b32 v141, v104 offset:5140
	ds_read_b32 v142, v104 offset:6168
	ds_read_b32 v143, v104 offset:7196
	s_waitcnt lgkmcnt(0)
	v_mov_b32_e32 v82, v186
	v_mov_b32_e32 v83, v187
	v_mov_b32_e32 v84, v188
	v_mov_b32_e32 v85, v189
	v_mov_b32_e32 v90, v190
	v_mov_b32_e32 v91, v191
	v_mov_b32_e32 v92, v192
	v_mov_b32_e32 v93, v193
	v_mov_b32_e32 v78, v194
	v_mov_b32_e32 v79, v195
	v_mov_b32_e32 v80, v196
	v_mov_b32_e32 v81, v197
	v_mov_b32_e32 v86, v198
	v_mov_b32_e32 v87, v199
	v_mov_b32_e32 v88, v200
	v_mov_b32_e32 v89, v201
	v_mul_f32_e32 v85, v143, v85
	v_mul_f32_e32 v90, v136, v90
	v_mul_f32_e32 v91, v137, v91
	v_mul_f32_e32 v92, v138, v92
	v_mul_f32_e32 v93, v139, v93
	v_mul_f32_e32 v94, v140, v82
	v_mul_f32_e32 v95, v141, v83
	v_mul_f32_e32 v96, v142, v84
	v_cvt_pk_bf16_f32 v82, v90, v91
	v_cvt_pk_bf16_f32 v83, v92, v93
	v_cvt_pk_bf16_f32 v84, v94, v95
	v_cvt_pk_bf16_f32 v85, v96, v85
	flat_store_dwordx4 v[126:127], v[82:85] offset:32
	ds_read_b32 v144, v104 offset:16448
	ds_read_b32 v145, v104 offset:17476
	ds_read_b32 v156, v104 offset:18504
	ds_read_b32 v157, v104 offset:19532
	ds_read_b32 v158, v104 offset:20560
	ds_read_b32 v159, v104 offset:21588
	ds_read_b32 v160, v104 offset:22616
	ds_read_b32 v161, v104 offset:23644
	s_waitcnt lgkmcnt(0)
	v_mov_b32_e32 v94, v212
	v_mov_b32_e32 v95, v213
	v_mov_b32_e32 v96, v214
	v_mov_b32_e32 v97, v215
	v_mov_b32_e32 v108, v216
	v_mov_b32_e32 v109, v217
	v_mov_b32_e32 v110, v218
	v_mov_b32_e32 v111, v219
	v_mov_b32_e32 v90, v220
	v_mov_b32_e32 v91, v221
	v_mov_b32_e32 v92, v222
	v_mov_b32_e32 v93, v223
	v_mov_b32_e32 v98, v224
	v_mov_b32_e32 v99, v225
	v_mov_b32_e32 v100, v226
	v_mov_b32_e32 v101, v227
	v_mul_f32_e32 v97, v161, v97
	v_mul_f32_e32 v105, v144, v108
	v_mul_f32_e32 v108, v145, v109
	v_mul_f32_e32 v109, v156, v110
	v_mul_f32_e32 v110, v157, v111
	v_mul_f32_e32 v111, v158, v94
	v_mul_f32_e32 v112, v159, v95
	v_mul_f32_e32 v113, v160, v96
	v_cvt_pk_bf16_f32 v94, v105, v108
	v_cvt_pk_bf16_f32 v95, v109, v110
	v_cvt_pk_bf16_f32 v96, v111, v112
	v_cvt_pk_bf16_f32 v97, v113, v97
	flat_store_dwordx4 v[126:127], v[94:97] offset:64
	ds_read_b32 v162, v104 offset:32896
	ds_read_b32 v163, v104 offset:33924
	ds_read_b32 v164, v104 offset:34952
	ds_read_b32 v165, v104 offset:35980
	ds_read_b32 v166, v104 offset:37008
	ds_read_b32 v167, v104 offset:38036
	ds_read_b32 v168, v104 offset:39064
	ds_read_b32 v169, v104 offset:40092
	s_nop 0
	s_waitcnt lgkmcnt(0)
	v_mov_b32_e32 v178, v228
	v_mov_b32_e32 v179, v229
	v_mov_b32_e32 v180, v230
	v_mov_b32_e32 v181, v231
	v_mov_b32_e32 v182, v232
	v_mov_b32_e32 v183, v233
	v_mov_b32_e32 v184, v234
	v_mov_b32_e32 v185, v235
	v_mov_b32_e32 v102, v236
	v_mov_b32_e32 v103, v237
	v_mov_b32_e32 v104, v238
	v_mov_b32_e32 v105, v239
	v_mov_b32_e32 v110, v240
	v_mov_b32_e32 v111, v241
	v_mov_b32_e32 v112, v242
	v_mov_b32_e32 v113, v243
	v_mul_f32_e32 v172, v166, v178
	v_mul_f32_e32 v106, v162, v182
	v_mul_f32_e32 v107, v163, v183
	v_mul_f32_e32 v108, v164, v184
	v_mul_f32_e32 v109, v165, v185
	v_mul_f32_e32 v173, v167, v179
	v_mul_f32_e32 v174, v168, v180
	v_mul_f32_e32 v175, v169, v181
	v_cvt_pk_bf16_f32 v106, v106, v107
	v_cvt_pk_bf16_f32 v107, v108, v109
	v_cvt_pk_bf16_f32 v108, v172, v173
	v_cvt_pk_bf16_f32 v109, v174, v175
	flat_store_dwordx4 v[126:127], v[106:109] offset:96
	v_add_u32_e32 v126, 0x2020, v155
	ds_write2_b32 v155, v18, v19 offset1:1
	ds_write2_b32 v155, v20, v21 offset0:2 offset1:3
	ds_write2_b32 v126, v26, v27 offset1:1
	v_add_u32_e32 v126, 0x2028, v155
	ds_write2_b32 v126, v28, v29 offset1:1
	v_add_u32_e32 v126, 0x4040, v155
	ds_write2_b32 v126, v34, v35 offset1:1
	v_add_u32_e32 v126, 0x4048, v155
	ds_write2_b32 v126, v36, v37 offset1:1
	v_add_u32_e32 v126, 0x6060, v155
	ds_write2_b32 v126, v42, v43 offset1:1
	v_add_u32_e32 v126, 0x6068, v155
	ds_write2_b32 v126, v44, v45 offset1:1
	v_add_u32_e32 v126, 0x8080, v155
	ds_write2_b32 v126, v50, v51 offset1:1
	v_add_u32_e32 v126, 0x8088, v155
	ds_write2_b32 v126, v52, v53 offset1:1
	v_add_u32_e32 v126, 0xa0a0, v155
	ds_write2_b32 v126, v54, v55 offset1:1
	v_add_u32_e32 v126, 0xa0a8, v155
	ds_write2_b32 v126, v56, v57 offset1:1
	v_add_u32_e32 v126, 0xc0c0, v155
	ds_write2_b32 v126, v58, v59 offset1:1
	v_add_u32_e32 v126, 0xc0c8, v155
	ds_write2_b32 v126, v60, v61 offset1:1
	v_add_u32_e32 v126, 0xe0e0, v155
	ds_write2_b32 v126, v62, v63 offset1:1
	v_add_u32_e32 v126, 0xe0e8, v155
	ds_write2_b32 v126, v64, v65 offset1:1
	s_waitcnt lgkmcnt(0)
	s_barrier
	s_cselect_b64 s[100:101], -1, 0
	s_cbranch_scc1 .LBB0_909
	s_lshl_b32 s2, s2, 6
	s_and_b32 s16, s20, 0x1c0
	s_and_b32 s2, s2, 0x7fffff00
	v_add_u32_e32 v62, s16, v146
	v_lshl_add_u64 v[58:59], s[2:3], 2, v[114:115]
	v_mad_i64_i32 v[18:19], s[16:17], v62, s30, v[58:59]
	v_add_u32_e32 v20, 8, v62
	v_add_u32_e32 v34, 16, v62
	v_add_u32_e32 v36, 24, v62
	v_add_u32_e32 v50, 32, v62
	v_add_u32_e32 v52, 40, v62
	v_add_u32_e32 v60, 48, v62
	v_add_u32_e32 v62, 56, v62
	v_mad_i64_i32 v[26:27], s[16:17], v20, s30, v[58:59]
	v_mad_i64_i32 v[34:35], s[16:17], v34, s30, v[58:59]
	v_mad_i64_i32 v[42:43], s[16:17], v36, s30, v[58:59]
	v_mad_i64_i32 v[50:51], s[16:17], v50, s30, v[58:59]
	v_mad_i64_i32 v[54:55], s[16:17], v52, s30, v[58:59]
	v_mad_i64_i32 v[60:61], s[16:17], v60, s30, v[58:59]
	v_mad_i64_i32 v[62:63], s[16:17], v62, s30, v[58:59]
.LBB0_909:
	v_mul_f32_e32 v74, v128, v74
	v_mul_f32_e32 v126, v129, v75
	v_mul_f32_e32 v66, v132, v66
	v_mul_f32_e32 v128, v133, v67
	v_mul_f32_e32 v68, v134, v68
	v_mul_f32_e32 v132, v135, v69
	v_lshlrev_b32_e32 v67, 16, v72
	v_and_b32_e32 v129, 0xffff0000, v72
	v_lshlrev_b32_e32 v69, 16, v73
	v_and_b32_e32 v133, 0xffff0000, v73
	v_mul_f32_e32 v76, v130, v76
	v_mul_f32_e32 v130, v131, v77
	v_lshlrev_b32_e32 v75, 16, v70
	v_and_b32_e32 v127, 0xffff0000, v70
	v_lshlrev_b32_e32 v77, 16, v71
	v_and_b32_e32 v131, 0xffff0000, v71
	v_mul_f32_e32 v70, v136, v86
	v_mul_f32_e32 v134, v137, v87
	v_mul_f32_e32 v86, v138, v88
	v_mul_f32_e32 v136, v139, v89
	v_lshlrev_b32_e32 v71, 16, v82
	v_and_b32_e32 v135, 0xffff0000, v82
	v_lshlrev_b32_e32 v87, 16, v83
	v_and_b32_e32 v137, 0xffff0000, v83
	v_pk_add_f32 v[66:67], v[66:67], v[128:129]
	v_pk_add_f32 v[68:69], v[68:69], v[132:133]
	v_mul_f32_e32 v72, v140, v78
	v_mul_f32_e32 v88, v141, v79
	v_mul_f32_e32 v78, v142, v80
	v_mul_f32_e32 v80, v143, v81
	v_lshlrev_b32_e32 v73, 16, v84
	v_and_b32_e32 v89, 0xffff0000, v84
	v_lshlrev_b32_e32 v79, 16, v85
	v_and_b32_e32 v81, 0xffff0000, v85
	v_pk_add_f32 v[66:67], v[66:67], v[68:69]
	v_pk_add_f32 v[68:69], v[70:71], v[134:135]
	v_pk_add_f32 v[70:71], v[86:87], v[136:137]
	v_mul_f32_e32 v82, v144, v98
	v_pk_add_f32 v[68:69], v[68:69], v[70:71]
	v_pk_add_f32 v[70:71], v[72:73], v[88:89]
	v_pk_add_f32 v[72:73], v[78:79], v[80:81]
	v_mul_f32_e32 v138, v145, v99
	v_mul_f32_e32 v98, v156, v100
	v_mul_f32_e32 v140, v157, v101
	v_lshlrev_b32_e32 v83, 16, v94
	v_and_b32_e32 v139, 0xffff0000, v94
	v_lshlrev_b32_e32 v99, 16, v95
	v_and_b32_e32 v141, 0xffff0000, v95
	v_pk_add_f32 v[74:75], v[74:75], v[126:127]
	v_pk_add_f32 v[76:77], v[76:77], v[130:131]
	v_pk_add_f32 v[70:71], v[70:71], v[72:73]
	s_add_i32 s2, s19, -3
	v_mul_f32_e32 v84, v158, v90
	v_mul_f32_e32 v100, v159, v91
	v_mul_f32_e32 v90, v160, v92
	v_mul_f32_e32 v92, v161, v93
	v_lshlrev_b32_e32 v85, 16, v96
	v_and_b32_e32 v101, 0xffff0000, v96
	v_lshlrev_b32_e32 v91, 16, v97
	v_and_b32_e32 v93, 0xffff0000, v97
	v_pk_add_f32 v[74:75], v[74:75], v[76:77]
	v_pk_add_f32 v[68:69], v[68:69], v[70:71]
	v_pk_add_f32 v[70:71], v[82:83], v[138:139]
	v_pk_add_f32 v[72:73], v[98:99], v[140:141]
	s_and_b32 s16, s2, 6
	v_pk_add_f32 v[66:67], v[74:75], v[66:67]
	v_pk_add_f32 v[70:71], v[70:71], v[72:73]
	v_pk_add_f32 v[72:73], v[84:85], v[100:101]
	v_pk_add_f32 v[74:75], v[90:91], v[92:93]
	v_mul_f32_e32 v94, v162, v110
	v_mul_f32_e32 v142, v163, v111
	v_mul_f32_e32 v110, v164, v112
	v_mul_f32_e32 v144, v165, v113
	v_lshlrev_b32_e32 v95, 16, v106
	v_and_b32_e32 v143, 0xffff0000, v106
	v_lshlrev_b32_e32 v111, 16, v107
	v_and_b32_e32 v145, 0xffff0000, v107
	s_lshl_b32 s2, s16, 6
	v_pk_add_f32 v[72:73], v[72:73], v[74:75]
	v_mul_f32_e32 v96, v166, v102
	v_mul_f32_e32 v112, v167, v103
	v_mul_f32_e32 v102, v168, v104
	v_mul_f32_e32 v104, v169, v105
	v_lshlrev_b32_e32 v97, 16, v108
	v_and_b32_e32 v113, 0xffff0000, v108
	v_lshlrev_b32_e32 v103, 16, v109
	v_and_b32_e32 v105, 0xffff0000, v109
	v_pk_add_f32 v[70:71], v[70:71], v[72:73]
	v_pk_add_f32 v[72:73], v[94:95], v[142:143]
	v_pk_add_f32 v[74:75], v[110:111], v[144:145]
	s_or_b32 s2, s2, s22
	v_pk_add_f32 v[72:73], v[72:73], v[74:75]
	v_pk_add_f32 v[74:75], v[96:97], v[112:113]
	v_pk_add_f32 v[76:77], v[102:103], v[104:105]
	v_pk_add_f32 v[66:67], v[122:123], v[66:67]
	s_lshl_b32 s17, s2, 1
	v_pk_add_f32 v[74:75], v[74:75], v[76:77]
	v_pk_add_f32 v[66:67], v[66:67], v[68:69]
	s_add_u32 s24, s42, s17
	v_pk_add_f32 v[72:73], v[72:73], v[74:75]
	v_pk_add_f32 v[66:67], v[66:67], v[70:71]
	s_addc_u32 s25, s43, 0
	s_lshl_b32 s2, s2, 2
	v_pk_add_f32 v[74:75], v[66:67], v[72:73]
	v_add_u32_e32 v66, v150, v152
	v_lshl_add_u64 v[94:95], v[116:117], 0, s[2:3]
	v_lshl_add_u64 v[92:93], v[118:119], 0, s[2:3]
	ds_read_b32 v85, v66
	ds_read_b32 v87, v66 offset:1028
	ds_read_b32 v89, v66 offset:2056
	ds_read_b32 v91, v66 offset:3084
	ds_read_b32 v98, v66 offset:4112
	ds_read_b32 v99, v66 offset:5140
	ds_read_b32 v100, v66 offset:6168
	ds_read_b32 v101, v66 offset:7196
	global_load_dwordx4 v[66:69], v[94:95], off offset:272
	global_load_dwordx4 v[70:73], v[94:95], off offset:256
	global_load_dwordx4 v[76:79], v[92:93], off offset:272
	global_load_dwordx4 v[80:83], v[92:93], off offset:256
	global_load_dwordx4 v[186:189], v[94:95], off offset:336
	global_load_dwordx4 v[190:193], v[94:95], off offset:320
	global_load_dwordx4 v[194:197], v[92:93], off offset:336
	global_load_dwordx4 v[198:201], v[92:93], off offset:320
	global_load_dwordx4 v[212:215], v[94:95], off offset:400
	global_load_dwordx4 v[216:219], v[94:95], off offset:384
	global_load_dwordx4 v[220:223], v[92:93], off offset:400
	global_load_dwordx4 v[224:227], v[92:93], off offset:384
	global_load_dwordx4 v[228:231], v[94:95], off offset:464
	global_load_dwordx4 v[232:235], v[94:95], off offset:448
	global_load_dwordx4 v[236:239], v[92:93], off offset:464
	global_load_dwordx4 v[240:243], v[92:93], off offset:448
	s_mov_b64 vcc, s[100:101]
	s_cbranch_vccnz .Lfold_skip_f2B
	global_load_dwordx4 v[18:21], v[18:19], off nt
	global_load_dwordx4 v[26:29], v[26:27], off nt
	global_load_dwordx4 v[34:37], v[34:35], off nt
	global_load_dwordx4 v[42:45], v[42:43], off nt
	global_load_dwordx4 v[50:53], v[50:51], off nt
	global_load_dwordx4 v[54:57], v[54:55], off nt
	global_load_dwordx4 v[58:61], v[60:61], off nt
	global_load_dwordx4 v[62:65], v[62:63], off nt
	s_waitcnt vmcnt(8)
	s_branch .Lfold_join_f2B

.Lfold_join_f2B:
	v_lshl_add_u64 v[96:97], s[24:25], 0, v[124:125]
	v_lshl_add_u64 v[96:97], v[96:97], 0, v[0:1]
	v_add_u32_e32 v138, v150, v153
	s_cmp_lg_u32 s16, 6
	s_waitcnt lgkmcnt(0)
	v_mul_f32_e32 v69, v101, v69
	v_mul_f32_e32 v70, v85, v70
	v_mul_f32_e32 v88, v85, v80
	v_mul_f32_e32 v90, v87, v81
	v_mul_f32_e32 v84, v89, v82
	v_mul_f32_e32 v80, v98, v76
	v_mul_f32_e32 v82, v99, v77
	v_mul_f32_e32 v76, v100, v78
	v_mul_f32_e32 v78, v101, v79
	v_mul_f32_e32 v71, v87, v71
	v_mul_f32_e32 v72, v89, v72
	v_mul_f32_e32 v73, v91, v73
	v_mul_f32_e32 v77, v98, v66
	v_mul_f32_e32 v79, v99, v67
	v_mul_f32_e32 v81, v100, v68
	v_cvt_pk_bf16_f32 v66, v70, v71
	v_cvt_pk_bf16_f32 v67, v72, v73
	v_cvt_pk_bf16_f32 v68, v77, v79
	v_cvt_pk_bf16_f32 v69, v81, v69
	flat_store_dwordx4 v[96:97], v[66:69] offset:128
	v_mul_f32_e32 v86, v91, v83
	v_lshlrev_b32_e32 v89, 16, v66
	v_and_b32_e32 v91, 0xffff0000, v66
	v_lshlrev_b32_e32 v85, 16, v67
	v_and_b32_e32 v87, 0xffff0000, v67
	v_lshlrev_b32_e32 v81, 16, v68
	v_and_b32_e32 v83, 0xffff0000, v68
	v_lshlrev_b32_e32 v77, 16, v69
	v_and_b32_e32 v79, 0xffff0000, v69
	ds_read_b32 v107, v138
	ds_read_b32 v109, v138 offset:1028
	ds_read_b32 v111, v138 offset:2056
	ds_read_b32 v113, v138 offset:3084
	ds_read_b32 v122, v138 offset:4112
	ds_read_b32 v123, v138 offset:5140
	ds_read_b32 v124, v138 offset:6168
	ds_read_b32 v125, v138 offset:7196
	v_pk_add_f32 v[88:89], v[88:89], v[90:91]
	v_pk_add_f32 v[84:85], v[84:85], v[86:87]
	v_pk_add_f32 v[80:81], v[80:81], v[82:83]
	v_pk_add_f32 v[76:77], v[76:77], v[78:79]
	v_pk_add_f32 v[84:85], v[88:89], v[84:85]
	v_pk_add_f32 v[76:77], v[80:81], v[76:77]
	s_waitcnt lgkmcnt(0)
	v_mov_b32_e32 v66, v186
	v_mov_b32_e32 v67, v187
	v_mov_b32_e32 v68, v188
	v_mov_b32_e32 v69, v189
	v_mov_b32_e32 v70, v190
	v_mov_b32_e32 v71, v191
	v_mov_b32_e32 v72, v192
	v_mov_b32_e32 v73, v193
	v_mov_b32_e32 v98, v194
	v_mov_b32_e32 v99, v195
	v_mov_b32_e32 v100, v196
	v_mov_b32_e32 v101, v197
	v_mov_b32_e32 v102, v198
	v_mov_b32_e32 v103, v199
	v_mov_b32_e32 v104, v200
	v_mov_b32_e32 v105, v201
	v_mul_f32_e32 v69, v125, v69
	v_mul_f32_e32 v70, v107, v70
	v_mul_f32_e32 v71, v109, v71
	v_mul_f32_e32 v110, v107, v102
	v_mul_f32_e32 v112, v109, v103
	v_mul_f32_e32 v106, v111, v104
	v_mul_f32_e32 v102, v122, v98
	v_mul_f32_e32 v104, v123, v99
	v_mul_f32_e32 v98, v124, v100
	v_mul_f32_e32 v100, v125, v101
	v_mul_f32_e32 v72, v111, v72
	v_mul_f32_e32 v73, v113, v73
	v_mul_f32_e32 v99, v122, v66
	v_mul_f32_e32 v101, v123, v67
	v_mul_f32_e32 v103, v124, v68
	v_cvt_pk_bf16_f32 v66, v70, v71
	v_cvt_pk_bf16_f32 v67, v72, v73
	v_cvt_pk_bf16_f32 v68, v99, v101
	v_cvt_pk_bf16_f32 v69, v103, v69
	flat_store_dwordx4 v[96:97], v[66:69] offset:160
	v_mul_f32_e32 v108, v113, v105
	v_lshlrev_b32_e32 v111, 16, v66
	v_and_b32_e32 v113, 0xffff0000, v66
	v_lshlrev_b32_e32 v107, 16, v67
	v_and_b32_e32 v109, 0xffff0000, v67
	v_lshlrev_b32_e32 v103, 16, v68
	v_and_b32_e32 v105, 0xffff0000, v68
	v_lshlrev_b32_e32 v99, 16, v69
	v_and_b32_e32 v101, 0xffff0000, v69
	ds_read_b32 v131, v138 offset:16448
	ds_read_b32 v133, v138 offset:17476
	ds_read_b32 v135, v138 offset:18504
	ds_read_b32 v137, v138 offset:19532
	ds_read_b32 v139, v138 offset:20560
	ds_read_b32 v140, v138 offset:21588
	ds_read_b32 v141, v138 offset:22616
	ds_read_b32 v142, v138 offset:23644
	v_pk_add_f32 v[76:77], v[84:85], v[76:77]
	v_pk_add_f32 v[78:79], v[106:107], v[108:109]
	v_pk_add_f32 v[74:75], v[74:75], v[76:77]
	v_pk_add_f32 v[76:77], v[110:111], v[112:113]
	v_pk_add_f32 v[80:81], v[98:99], v[100:101]
	v_pk_add_f32 v[76:77], v[76:77], v[78:79]
	v_pk_add_f32 v[78:79], v[102:103], v[104:105]
	s_waitcnt lgkmcnt(0)
	v_mov_b32_e32 v66, v212
	v_mov_b32_e32 v67, v213
	v_mov_b32_e32 v68, v214
	v_mov_b32_e32 v69, v215
	v_mov_b32_e32 v70, v216
	v_mov_b32_e32 v71, v217
	v_mov_b32_e32 v72, v218
	v_mov_b32_e32 v73, v219
	v_mov_b32_e32 v122, v220
	v_mov_b32_e32 v123, v221
	v_mov_b32_e32 v124, v222
	v_mov_b32_e32 v125, v223
	v_mov_b32_e32 v126, v224
	v_mov_b32_e32 v127, v225
	v_mov_b32_e32 v128, v226
	v_mov_b32_e32 v129, v227
	v_mul_f32_e32 v69, v142, v69
	v_mul_f32_e32 v70, v131, v70
	v_mul_f32_e32 v71, v133, v71
	v_mul_f32_e32 v134, v131, v126
	v_mul_f32_e32 v136, v133, v127
	v_mul_f32_e32 v130, v135, v128
	v_mul_f32_e32 v126, v139, v122
	v_mul_f32_e32 v128, v140, v123
	v_mul_f32_e32 v122, v141, v124
	v_mul_f32_e32 v124, v142, v125
	v_mul_f32_e32 v72, v135, v72
	v_mul_f32_e32 v73, v137, v73
	v_mul_f32_e32 v123, v139, v66
	v_mul_f32_e32 v125, v140, v67
	v_mul_f32_e32 v127, v141, v68
	v_cvt_pk_bf16_f32 v66, v70, v71
	v_cvt_pk_bf16_f32 v67, v72, v73
	v_cvt_pk_bf16_f32 v68, v123, v125
	v_cvt_pk_bf16_f32 v69, v127, v69
	flat_store_dwordx4 v[96:97], v[66:69] offset:192
	v_mul_f32_e32 v132, v137, v129
	v_lshlrev_b32_e32 v135, 16, v66
	v_and_b32_e32 v137, 0xffff0000, v66
	v_lshlrev_b32_e32 v131, 16, v67
	v_and_b32_e32 v133, 0xffff0000, v67
	v_lshlrev_b32_e32 v127, 16, v68
	v_and_b32_e32 v129, 0xffff0000, v68
	v_lshlrev_b32_e32 v123, 16, v69
	v_and_b32_e32 v125, 0xffff0000, v69
	ds_read_b32 v139, v138 offset:32896
	ds_read_b32 v141, v138 offset:33924
	ds_read_b32 v160, v138 offset:34952
	ds_read_b32 v161, v138 offset:35980
	ds_read_b32 v162, v138 offset:37008
	ds_read_b32 v163, v138 offset:38036
	ds_read_b32 v164, v138 offset:39064
	ds_read_b32 v165, v138 offset:40092
	v_pk_add_f32 v[78:79], v[78:79], v[80:81]
	v_pk_add_f32 v[80:81], v[122:123], v[124:125]
	v_pk_add_f32 v[76:77], v[76:77], v[78:79]
	v_pk_add_f32 v[78:79], v[130:131], v[132:133]
	v_pk_add_f32 v[74:75], v[74:75], v[76:77]
	v_pk_add_f32 v[76:77], v[134:135], v[136:137]
	s_waitcnt lgkmcnt(0)
	v_mov_b32_e32 v142, v228
	v_mov_b32_e32 v143, v229
	v_mov_b32_e32 v144, v230
	v_mov_b32_e32 v145, v231
	v_mov_b32_e32 v156, v232
	v_mov_b32_e32 v157, v233
	v_mov_b32_e32 v158, v234
	v_mov_b32_e32 v159, v235
	v_mov_b32_e32 v66, v236
	v_mov_b32_e32 v67, v237
	v_mov_b32_e32 v68, v238
	v_mov_b32_e32 v69, v239
	v_mov_b32_e32 v70, v240
	v_mov_b32_e32 v71, v241
	v_mov_b32_e32 v72, v242
	v_mov_b32_e32 v73, v243
	v_mul_f32_e32 v93, v162, v142
	v_pk_add_f32 v[76:77], v[76:77], v[78:79]
	v_pk_add_f32 v[78:79], v[126:127], v[128:129]
	v_mul_f32_e32 v138, v139, v70
	v_mul_f32_e32 v140, v141, v71
	v_mul_f32_e32 v92, v160, v72
	v_mul_f32_e32 v94, v161, v73
	v_mul_f32_e32 v70, v162, v66
	v_mul_f32_e32 v72, v163, v67
	v_mul_f32_e32 v66, v164, v68
	v_mul_f32_e32 v68, v165, v69
	v_mul_f32_e32 v67, v139, v156
	v_mul_f32_e32 v69, v141, v157
	v_mul_f32_e32 v71, v160, v158
	v_mul_f32_e32 v73, v161, v159
	v_mul_f32_e32 v95, v163, v143
	v_mul_f32_e32 v139, v164, v144
	v_mul_f32_e32 v141, v165, v145
	v_pk_add_f32 v[78:79], v[78:79], v[80:81]
	v_cvt_pk_bf16_f32 v142, v67, v69
	v_cvt_pk_bf16_f32 v143, v71, v73
	v_cvt_pk_bf16_f32 v144, v93, v95
	v_cvt_pk_bf16_f32 v145, v139, v141
	flat_store_dwordx4 v[96:97], v[142:145] offset:224
	v_lshlrev_b32_e32 v139, 16, v142
	v_and_b32_e32 v141, 0xffff0000, v142
	v_lshlrev_b32_e32 v93, 16, v143
	v_and_b32_e32 v95, 0xffff0000, v143
	v_lshlrev_b32_e32 v71, 16, v144
	v_and_b32_e32 v73, 0xffff0000, v144
	v_lshlrev_b32_e32 v67, 16, v145
	v_and_b32_e32 v69, 0xffff0000, v145
	v_pk_add_f32 v[76:77], v[76:77], v[78:79]
	v_pk_add_f32 v[78:79], v[92:93], v[94:95]
	v_pk_add_f32 v[74:75], v[74:75], v[76:77]
	v_pk_add_f32 v[76:77], v[138:139], v[140:141]
	v_pk_add_f32 v[70:71], v[70:71], v[72:73]
	v_pk_add_f32 v[66:67], v[66:67], v[68:69]
	v_pk_add_f32 v[76:77], v[76:77], v[78:79]
	v_pk_add_f32 v[66:67], v[70:71], v[66:67]
	s_nop 0
	v_pk_add_f32 v[66:67], v[76:77], v[66:67]
	s_nop 0
	v_pk_add_f32 v[122:123], v[74:75], v[66:67]
	s_cbranch_scc1 .LBB0_904
	ds_bpermute_b32 v66, v151, v123
	ds_bpermute_b32 v67, v151, v122
	s_and_saveexec_b64 s[16:17], s[0:1]
	s_cbranch_execz .LBB0_903
	s_lshr_b32 s2, s22, 9
	s_mulk_i32 s2, 0x7800
	s_add_u32 s22, s4, s2
	s_addc_u32 s23, s5, 0
	s_waitcnt lgkmcnt(0)
	v_add_f32_e32 v68, v122, v67
	v_add_f32_e32 v69, v123, v66
	v_lshl_add_u64 v[66:67], v[120:121], 2, s[22:23]
	flat_store_dword v[66:67], v69
	v_add_co_u32_e32 v66, vcc, 0x1e000, v66
	s_nop 1
	v_addc_co_u32_e32 v67, vcc, 0, v67, vcc
	flat_store_dword v[66:67], v68
	s_branch .LBB0_903

; #define LAS __attribute__((address_space(3)))
; __global__ void __launch_bounds__(512, 2) fwd_kernel(Params p) {
;     extern __shared__ __attribute__((aligned(16))) unsigned char lds_raw[];
;     LAS unsigned char* lds = (LAS unsigned char*)lds_raw;
;     cg::grid_group grid = cg::this_grid();
;     volatile LAS unsigned* xb_st = (volatile LAS unsigned*)(lds + LDS_BYTES - 16);
;     if (threadIdx.x == 0) { xb_st[0] = 0u; xb_st[1] = 0u; }
;     __syncthreads();
;     const XcdBarrier xbar = xcd_barrier_post((unsigned*)(p.ws + WS_BAR), xb_st);
	.amdhsa_kernel _Z10fwd_kernel6Params
		.amdhsa_group_segment_fixed_size 0
		.amdhsa_private_segment_fixed_size 0
		.amdhsa_kernarg_size 464
		.amdhsa_user_sgpr_count 2
		.amdhsa_user_sgpr_dispatch_ptr 0
		.amdhsa_user_sgpr_queue_ptr 0
		.amdhsa_user_sgpr_kernarg_segment_ptr 1
		.amdhsa_user_sgpr_dispatch_id 0
		.amdhsa_user_sgpr_kernarg_preload_length 0
		.amdhsa_user_sgpr_kernarg_preload_offset 0
		.amdhsa_user_sgpr_private_segment_size 0
		.amdhsa_uses_dynamic_stack 0
		.amdhsa_enable_private_segment 0
		.amdhsa_system_sgpr_workgroup_id_x 1
		.amdhsa_system_sgpr_workgroup_id_y 0
		.amdhsa_system_sgpr_workgroup_id_z 0
		.amdhsa_system_sgpr_workgroup_info 0
		.amdhsa_system_vgpr_workitem_id 2
		.amdhsa_next_free_vgpr 256
		.amdhsa_next_free_sgpr 102
		.amdhsa_accum_offset 256
		.amdhsa_reserve_vcc 1
		.amdhsa_float_round_mode_32 0
		.amdhsa_float_round_mode_16_64 0
		.amdhsa_float_denorm_mode_32 3
		.amdhsa_float_denorm_mode_16_64 3
		.amdhsa_dx10_clamp 1
		.amdhsa_ieee_mode 1
		.amdhsa_fp16_overflow 0
		.amdhsa_tg_split 0
		.amdhsa_exception_fp_ieee_invalid_op 0
		.amdhsa_exception_fp_denorm_src 0
		.amdhsa_exception_fp_ieee_div_zero 0
		.amdhsa_exception_fp_ieee_overflow 0
		.amdhsa_exception_fp_ieee_underflow 0
		.amdhsa_exception_fp_ieee_inexact 0
		.amdhsa_exception_int_div_zero 0
	.end_amdhsa_kernel

; #define LAS __attribute__((address_space(3)))
; __global__ void __launch_bounds__(512, 2) fwd_kernel(Params p) {
;     extern __shared__ __attribute__((aligned(16))) unsigned char lds_raw[];
;     LAS unsigned char* lds = (LAS unsigned char*)lds_raw;
;     cg::grid_group grid = cg::this_grid();
;     volatile LAS unsigned* xb_st = (volatile LAS unsigned*)(lds + LDS_BYTES - 16);
amdhsa.kernels:
  - .agpr_count:     0
    .args:
      - .offset:         0
        .size:           208
        .value_kind:     by_value
      - .offset:         208
        .size:           4
        .value_kind:     hidden_block_count_x
      - .offset:         212
        .size:           4
        .value_kind:     hidden_block_count_y
      - .offset:         216
        .size:           4
        .value_kind:     hidden_block_count_z
      - .offset:         220
        .size:           2
        .value_kind:     hidden_group_size_x
      - .offset:         222
        .size:           2
        .value_kind:     hidden_group_size_y
      - .offset:         224
        .size:           2
        .value_kind:     hidden_group_size_z
      - .offset:         226
        .size:           2
        .value_kind:     hidden_remainder_x
      - .offset:         228
        .size:           2
        .value_kind:     hidden_remainder_y
      - .offset:         230
        .size:           2
        .value_kind:     hidden_remainder_z
      - .offset:         248
        .size:           8
        .value_kind:     hidden_global_offset_x
      - .offset:         256
        .size:           8
        .value_kind:     hidden_global_offset_y
      - .offset:         264
        .size:           8
        .value_kind:     hidden_global_offset_z
      - .offset:         272
        .size:           2
        .value_kind:     hidden_grid_dims
      - .offset:         296
        .size:           8
        .value_kind:     hidden_multigrid_sync_arg
      - .offset:         328
        .size:           4
        .value_kind:     hidden_dynamic_lds_size
    .group_segment_fixed_size: 0
    .kernarg_segment_align: 8
    .kernarg_segment_size: 464
    .language:       OpenCL C
    .language_version:
      - 2
      - 0
    .max_flat_workgroup_size: 512
    .name:           _Z10fwd_kernel6Params
    .private_segment_fixed_size: 0
    .sgpr_count:     108
    .sgpr_spill_count: 389
    .symbol:         _Z10fwd_kernel6Params.kd
    .uniform_work_group_size: 1
    .uses_dynamic_stack: false
    .vgpr_count:     256
    .vgpr_spill_count: 0
    .wavefront_size: 64
